# gated-sum (G4) epilogue rewritten: two straight-line versions, gate-tile loads six row groups ahead with counted vmcnt
# speedup vs baseline: 1.0166x; 1.0038x over previous
; #define GAS __attribute__((address_space(1)))
; __device__ __forceinline__ float fast_rcp(float x) { return __builtin_amdgcn_rcpf(x); }
; __device__ __forceinline__ v4u tr4(int a, v4u x) { return (v4u){bperm(a, x.x), bperm(a, x.y), bperm(a, x.z), bperm(a, x.w)}; }
; __device__ __forceinline__ v4u pack8(const f32x4& a, const f32x4& b) { return (v4u){pg8::cvt_pk_bf16(a[0], a[1]), pg8::cvt_pk_bf16(a[2], a[3]), pg8::cvt_pk_bf16(b[0], b[1]), pg8::cvt_pk_bf16(b[2], b[3])}; }
;     __device__ __forceinline__ bool operator()(AccT& acc, const Unit& u, int wr, int wc, int fr, int fq) const {
;     ...
;         const int n = u.pm / NPANEL, pm = u.pm - n * NPANEL, pn = u.pn & 3;
;         const int row0 = pm * 256 + wr * 64 + t.tfr, col0 = pn * 256 + wc * 32 + 8 * t.tfq;
; #pragma unroll
;         for (int ai = 0; ai < 2; ++ai)
; #pragma unroll
;             for (int m = 0; m < 4; ++m) { const size_t r = (size_t)(row0 + ai * 128 + m * 16);
; #pragma unroll
;                 for (int bj = 0; bj < 2; ++bj) {
;                     const v4u ga = tr4(t.push, *(const GAS v4u*)(Gt + r * (3 * D) + n * D + col0 + bj * 128));
;                     float f[8] = {bflo(ga.x), bfhi(ga.x), bflo(ga.y), bfhi(ga.y), bflo(ga.z), bfhi(ga.z), bflo(ga.w), bfhi(ga.w)};
;                     if (n < 2) { const v4u gb = tr4(t.push, *(const GAS v4u*)(Gt + r * (3 * D) + (n + 1) * D + col0 + bj * 128));
;                         const float h[8] = {bflo(gb.x), bfhi(gb.x), bflo(gb.y), bfhi(gb.y), bflo(gb.z), bfhi(gb.z), bflo(gb.w), bfhi(gb.w)};
; #pragma unroll
;                         for (int e = 0; e < 8; ++e) f[e] = f[e] * fast_rcp(fmaxf(h[e], 1e-30f)); }
;                     f32x4 v0 = acc[ai][bj][m][0], v1 = acc[ai][bj][m][1];
;                     v0 = v0 * (f32x4){f[0], f[1], f[2], f[3]}; v1 = v1 * (f32x4){f[4], f[5], f[6], f[7]};
;                     acc[ai][bj][m][0] = v0; acc[ai][bj][m][1] = v1;
;                     if (n == 2) *(GAS v4u*)(mix + r * D + col0 + bj * 128) = tr4(t.pull, pack8(v0, v1));
.LBB0_1688:
	s_mul_hi_i32 s13, s8, 0xfe03f81
	s_lshr_b32 s15, s13, 31
	s_ashr_i32 s13, s13, 4
	s_add_i32 s13, s13, s15
	s_mov_b32 s9, s42
	v_mov_b32_e32 v145, v162
	s_mov_b32 s11, s36
	v_mov_b32_e32 v158, v1
	s_mul_i32 s15, s13, 0xfffffefe
	s_add_i32 s15, s15, s8
	s_lshl_b32 s10, s10, 8
	v_lshl_add_u32 v148, v145, 4, v158
	s_lshl_b32 s15, s15, 8
	s_lshl_b32 s11, s11, 6
	s_and_b32 s10, s10, 0x300
	s_lshl_b32 s9, s9, 5
	v_ashrrev_i32_e32 v142, 2, v148
	v_and_b32_e32 v149, 3, v158
	s_add_i32 s9, s9, s10
	s_add_i32 s11, s11, s15
	v_lshl_or_b32 v146, v149, 3, s9
	v_add_u32_e32 v144, s11, v142
	s_lshl_b32 s22, s13, 10
	v_mov_b64_e32 v[142:143], s[86:87]
	s_ashr_i32 s23, s22, 31
	v_ashrrev_i32_e32 v147, 31, v146
	v_mad_i64_i32 v[150:151], s[10:11], v144, s73, v[142:143]
	v_lshl_add_u64 v[152:153], s[22:23], 1, v[150:151]
	v_lshlrev_b64 v[142:143], 1, v[146:147]
	v_lshl_add_u64 v[152:153], v[152:153], 0, v[142:143]
	v_lshlrev_b32_e32 v158, 4, v158
	v_lshl_add_u32 v165, v145, 2, v158
	s_cmpk_gt_i32 s8, 0x203
	s_cselect_b64 s[20:21], -1, 0
	v_readlane_b32 s8, v253, 57
	v_ashrrev_i32_e32 v145, 31, v144
	v_and_b32_e32 v148, -4, v148
	v_readlane_b32 s9, v253, 58
	v_lshl_add_u32 v143, v149, 6, v148
	v_lshlrev_b64 v[148:149], 11, v[144:145]
	v_lshl_add_u64 v[146:147], v[146:147], 1, s[8:9]
	v_lshl_add_u64 v[148:149], v[146:147], 0, v[148:149]
	s_and_b64 vcc, exec, s[20:21]
	s_cbranch_vccnz .Lgate_epi_store
	v_mov_b64_e32 v[146:147], v[152:153]
	global_load_dwordx4 v[166:169], v[146:147], off
	global_load_dwordx4 v[170:173], v[146:147], off offset:2048
	global_load_dwordx4 v[174:177], v[146:147], off offset:256
	global_load_dwordx4 v[178:181], v[146:147], off offset:2304
	s_mov_b64 s[100:101], 0x18000
	v_lshl_add_u64 v[146:147], v[152:153], 0, s[100:101]
	global_load_dwordx4 v[182:185], v[146:147], off
	global_load_dwordx4 v[186:189], v[146:147], off offset:2048
	global_load_dwordx4 v[190:193], v[146:147], off offset:256
	global_load_dwordx4 v[194:197], v[146:147], off offset:2304
	s_mov_b64 s[100:101], 0x30000
	v_lshl_add_u64 v[146:147], v[152:153], 0, s[100:101]
	global_load_dwordx4 v[198:201], v[146:147], off
	global_load_dwordx4 v[202:205], v[146:147], off offset:2048
	global_load_dwordx4 v[206:209], v[146:147], off offset:256
	global_load_dwordx4 v[210:213], v[146:147], off offset:2304
	s_waitcnt vmcnt(10)
	ds_bpermute_b32 v166, v165, v166
	ds_bpermute_b32 v170, v165, v170
	ds_bpermute_b32 v167, v165, v167
	ds_bpermute_b32 v171, v165, v171
	ds_bpermute_b32 v168, v165, v168
	ds_bpermute_b32 v172, v165, v172
	ds_bpermute_b32 v169, v165, v169
	ds_bpermute_b32 v173, v165, v173
	s_waitcnt lgkmcnt(6)
	v_lshlrev_b32_e32 v160, 16, v170
	v_and_b32_e32 v161, 0xffff0000, v170
	v_lshlrev_b32_e32 v150, 16, v166
	v_and_b32_e32 v151, 0xffff0000, v166
	v_max_f32_e32 v160, v160, v160
	v_max_f32_e32 v161, v161, v161
	v_max_f32_e32 v160, 0xda24260, v160
	v_max_f32_e32 v161, 0xda24260, v161
	v_rcp_f32_e32 v160, v160
	v_rcp_f32_e32 v161, v161
	s_nop 0
	v_pk_mul_f32 v[150:151], v[160:161], v[150:151]
	v_pk_mul_f32 v[126:127], v[126:127], v[150:151]
	s_waitcnt lgkmcnt(4)
	v_lshlrev_b32_e32 v214, 16, v171
	v_and_b32_e32 v215, 0xffff0000, v171
	v_lshlrev_b32_e32 v154, 16, v167
	v_and_b32_e32 v155, 0xffff0000, v167
	v_max_f32_e32 v214, v214, v214
	v_max_f32_e32 v215, v215, v215
	v_max_f32_e32 v214, 0xda24260, v214
	v_max_f32_e32 v215, 0xda24260, v215
	v_rcp_f32_e32 v214, v214
	v_rcp_f32_e32 v215, v215
	s_nop 0
	v_pk_mul_f32 v[154:155], v[214:215], v[154:155]
	v_pk_mul_f32 v[128:129], v[128:129], v[154:155]
	s_waitcnt lgkmcnt(2)
	v_lshlrev_b32_e32 v216, 16, v172
	v_and_b32_e32 v217, 0xffff0000, v172
	v_lshlrev_b32_e32 v156, 16, v168
	v_and_b32_e32 v157, 0xffff0000, v168
	v_max_f32_e32 v216, v216, v216
	v_max_f32_e32 v217, v217, v217
	v_max_f32_e32 v216, 0xda24260, v216
	v_max_f32_e32 v217, 0xda24260, v217
	v_rcp_f32_e32 v216, v216
	v_rcp_f32_e32 v217, v217
	s_nop 0
	v_pk_mul_f32 v[156:157], v[216:217], v[156:157]
	v_pk_mul_f32 v[122:123], v[122:123], v[156:157]
	s_waitcnt lgkmcnt(0)
	v_lshlrev_b32_e32 v160, 16, v173
	v_and_b32_e32 v161, 0xffff0000, v173
	v_lshlrev_b32_e32 v158, 16, v169
	v_and_b32_e32 v159, 0xffff0000, v169
	v_max_f32_e32 v160, v160, v160
	v_max_f32_e32 v161, v161, v161
	v_max_f32_e32 v160, 0xda24260, v160
	v_max_f32_e32 v161, 0xda24260, v161
	v_rcp_f32_e32 v160, v160
	v_rcp_f32_e32 v161, v161
	s_nop 0
	v_pk_mul_f32 v[158:159], v[160:161], v[158:159]
	v_pk_mul_f32 v[124:125], v[124:125], v[158:159]
	s_mov_b64 s[100:101], 0x48000
	v_lshl_add_u64 v[146:147], v[152:153], 0, s[100:101]
	global_load_dwordx4 v[166:169], v[146:147], off
	global_load_dwordx4 v[170:173], v[146:147], off offset:2048
	s_waitcnt vmcnt(10)
	ds_bpermute_b32 v174, v165, v174
	ds_bpermute_b32 v178, v165, v178
	ds_bpermute_b32 v175, v165, v175
	ds_bpermute_b32 v179, v165, v179
	ds_bpermute_b32 v176, v165, v176
	ds_bpermute_b32 v180, v165, v180
	ds_bpermute_b32 v177, v165, v177
	ds_bpermute_b32 v181, v165, v181
	s_waitcnt lgkmcnt(6)
	v_lshlrev_b32_e32 v160, 16, v178
	v_and_b32_e32 v161, 0xffff0000, v178
	v_lshlrev_b32_e32 v150, 16, v174
	v_and_b32_e32 v151, 0xffff0000, v174
	v_max_f32_e32 v160, v160, v160
	v_max_f32_e32 v161, v161, v161
	v_max_f32_e32 v160, 0xda24260, v160
	v_max_f32_e32 v161, 0xda24260, v161
	v_rcp_f32_e32 v160, v160
	v_rcp_f32_e32 v161, v161
	s_nop 0
	v_pk_mul_f32 v[150:151], v[160:161], v[150:151]
	v_pk_mul_f32 v[94:95], v[94:95], v[150:151]
	s_waitcnt lgkmcnt(4)
; #define GAS __attribute__((address_space(1)))
; __device__ __forceinline__ float fast_rcp(float x) { return __builtin_amdgcn_rcpf(x); }
; __device__ __forceinline__ v4u tr4(int a, v4u x) { return (v4u){bperm(a, x.x), bperm(a, x.y), bperm(a, x.z), bperm(a, x.w)}; }
;     __device__ __forceinline__ bool operator()(AccT& acc, const Unit& u, int wr, int wc, int fr, int fq) const {
;     ...
;                     const v4u ga = tr4(t.push, *(const GAS v4u*)(Gt + r * (3 * D) + n * D + col0 + bj * 128));
;                     float f[8] = {bflo(ga.x), bfhi(ga.x), bflo(ga.y), bfhi(ga.y), bflo(ga.z), bfhi(ga.z), bflo(ga.w), bfhi(ga.w)};
;                     if (n < 2) { const v4u gb = tr4(t.push, *(const GAS v4u*)(Gt + r * (3 * D) + (n + 1) * D + col0 + bj * 128));
;                         const float h[8] = {bflo(gb.x), bfhi(gb.x), bflo(gb.y), bfhi(gb.y), bflo(gb.z), bfhi(gb.z), bflo(gb.w), bfhi(gb.w)};
; #pragma unroll
;                         for (int e = 0; e < 8; ++e) f[e] = f[e] * fast_rcp(fmaxf(h[e], 1e-30f)); }
;                     f32x4 v0 = acc[ai][bj][m][0], v1 = acc[ai][bj][m][1];
;                     v0 = v0 * (f32x4){f[0], f[1], f[2], f[3]}; v1 = v1 * (f32x4){f[4], f[5], f[6], f[7]};
;                     acc[ai][bj][m][0] = v0; acc[ai][bj][m][1] = v1;
	v_lshlrev_b32_e32 v214, 16, v179
	v_and_b32_e32 v215, 0xffff0000, v179
	v_lshlrev_b32_e32 v154, 16, v175
	v_and_b32_e32 v155, 0xffff0000, v175
	v_max_f32_e32 v214, v214, v214
	v_max_f32_e32 v215, v215, v215
	v_max_f32_e32 v214, 0xda24260, v214
	v_max_f32_e32 v215, 0xda24260, v215
	v_rcp_f32_e32 v214, v214
	v_rcp_f32_e32 v215, v215
	s_nop 0
	v_pk_mul_f32 v[154:155], v[214:215], v[154:155]
	v_pk_mul_f32 v[96:97], v[96:97], v[154:155]
	s_waitcnt lgkmcnt(2)
	v_lshlrev_b32_e32 v216, 16, v180
	v_and_b32_e32 v217, 0xffff0000, v180
	v_lshlrev_b32_e32 v156, 16, v176
	v_and_b32_e32 v157, 0xffff0000, v176
	v_max_f32_e32 v216, v216, v216
	v_max_f32_e32 v217, v217, v217
	v_max_f32_e32 v216, 0xda24260, v216
	v_max_f32_e32 v217, 0xda24260, v217
	v_rcp_f32_e32 v216, v216
	v_rcp_f32_e32 v217, v217
	s_nop 0
	v_pk_mul_f32 v[156:157], v[216:217], v[156:157]
	v_pk_mul_f32 v[90:91], v[90:91], v[156:157]
	s_waitcnt lgkmcnt(0)
	v_lshlrev_b32_e32 v160, 16, v181
	v_and_b32_e32 v161, 0xffff0000, v181
	v_lshlrev_b32_e32 v158, 16, v177
	v_and_b32_e32 v159, 0xffff0000, v177
	v_max_f32_e32 v160, v160, v160
	v_max_f32_e32 v161, v161, v161
	v_max_f32_e32 v160, 0xda24260, v160
	v_max_f32_e32 v161, 0xda24260, v161
	v_rcp_f32_e32 v160, v160
	v_rcp_f32_e32 v161, v161
	s_nop 0
	v_pk_mul_f32 v[158:159], v[160:161], v[158:159]
	v_pk_mul_f32 v[92:93], v[92:93], v[158:159]
	global_load_dwordx4 v[174:177], v[146:147], off offset:256
	global_load_dwordx4 v[178:181], v[146:147], off offset:2304
	s_waitcnt vmcnt(10)
	ds_bpermute_b32 v182, v165, v182
	ds_bpermute_b32 v186, v165, v186
	ds_bpermute_b32 v183, v165, v183
	ds_bpermute_b32 v187, v165, v187
	ds_bpermute_b32 v184, v165, v184
	ds_bpermute_b32 v188, v165, v188
	ds_bpermute_b32 v185, v165, v185
	ds_bpermute_b32 v189, v165, v189
	s_waitcnt lgkmcnt(6)
	v_lshlrev_b32_e32 v160, 16, v186
	v_and_b32_e32 v161, 0xffff0000, v186
	v_lshlrev_b32_e32 v150, 16, v182
	v_and_b32_e32 v151, 0xffff0000, v182
	v_max_f32_e32 v160, v160, v160
	v_max_f32_e32 v161, v161, v161
	v_max_f32_e32 v160, 0xda24260, v160
	v_max_f32_e32 v161, 0xda24260, v161
	v_rcp_f32_e32 v160, v160
	v_rcp_f32_e32 v161, v161
	s_nop 0
	v_pk_mul_f32 v[150:151], v[160:161], v[150:151]
	v_pk_mul_f32 v[118:119], v[118:119], v[150:151]
	s_waitcnt lgkmcnt(4)
	v_lshlrev_b32_e32 v214, 16, v187
	v_and_b32_e32 v215, 0xffff0000, v187
	v_lshlrev_b32_e32 v154, 16, v183
	v_and_b32_e32 v155, 0xffff0000, v183
	v_max_f32_e32 v214, v214, v214
	v_max_f32_e32 v215, v215, v215
	v_max_f32_e32 v214, 0xda24260, v214
	v_max_f32_e32 v215, 0xda24260, v215
	v_rcp_f32_e32 v214, v214
	v_rcp_f32_e32 v215, v215
	s_nop 0
	v_pk_mul_f32 v[154:155], v[214:215], v[154:155]
	v_pk_mul_f32 v[120:121], v[120:121], v[154:155]
	s_waitcnt lgkmcnt(2)
	v_lshlrev_b32_e32 v216, 16, v188
	v_and_b32_e32 v217, 0xffff0000, v188
	v_lshlrev_b32_e32 v156, 16, v184
	v_and_b32_e32 v157, 0xffff0000, v184
	v_max_f32_e32 v216, v216, v216
	v_max_f32_e32 v217, v217, v217
	v_max_f32_e32 v216, 0xda24260, v216
	v_max_f32_e32 v217, 0xda24260, v217
	v_rcp_f32_e32 v216, v216
	v_rcp_f32_e32 v217, v217
	s_nop 0
	v_pk_mul_f32 v[156:157], v[216:217], v[156:157]
	v_pk_mul_f32 v[114:115], v[114:115], v[156:157]
	s_waitcnt lgkmcnt(0)
	v_lshlrev_b32_e32 v160, 16, v189
	v_and_b32_e32 v161, 0xffff0000, v189
	v_lshlrev_b32_e32 v158, 16, v185
	v_and_b32_e32 v159, 0xffff0000, v185
	v_max_f32_e32 v160, v160, v160
	v_max_f32_e32 v161, v161, v161
	v_max_f32_e32 v160, 0xda24260, v160
	v_max_f32_e32 v161, 0xda24260, v161
	v_rcp_f32_e32 v160, v160
	v_rcp_f32_e32 v161, v161
	s_nop 0
	v_pk_mul_f32 v[158:159], v[160:161], v[158:159]
	v_pk_mul_f32 v[116:117], v[116:117], v[158:159]
	s_mov_b64 s[100:101], 0xc0000
	v_lshl_add_u64 v[146:147], v[152:153], 0, s[100:101]
	global_load_dwordx4 v[182:185], v[146:147], off
	global_load_dwordx4 v[186:189], v[146:147], off offset:2048
	s_waitcnt vmcnt(10)
	ds_bpermute_b32 v190, v165, v190
	ds_bpermute_b32 v194, v165, v194
	ds_bpermute_b32 v191, v165, v191
	ds_bpermute_b32 v195, v165, v195
	ds_bpermute_b32 v192, v165, v192
	ds_bpermute_b32 v196, v165, v196
	ds_bpermute_b32 v193, v165, v193
	ds_bpermute_b32 v197, v165, v197
	s_waitcnt lgkmcnt(6)
	v_lshlrev_b32_e32 v160, 16, v194
	v_and_b32_e32 v161, 0xffff0000, v194
	v_lshlrev_b32_e32 v150, 16, v190
	v_and_b32_e32 v151, 0xffff0000, v190
	v_max_f32_e32 v160, v160, v160
	v_max_f32_e32 v161, v161, v161
	v_max_f32_e32 v160, 0xda24260, v160
	v_max_f32_e32 v161, 0xda24260, v161
	v_rcp_f32_e32 v160, v160
	v_rcp_f32_e32 v161, v161
	s_nop 0
	v_pk_mul_f32 v[150:151], v[160:161], v[150:151]
	v_pk_mul_f32 v[86:87], v[86:87], v[150:151]
	s_waitcnt lgkmcnt(4)
	v_lshlrev_b32_e32 v214, 16, v195
	v_and_b32_e32 v215, 0xffff0000, v195
	v_lshlrev_b32_e32 v154, 16, v191
	v_and_b32_e32 v155, 0xffff0000, v191
	v_max_f32_e32 v214, v214, v214
	v_max_f32_e32 v215, v215, v215
	v_max_f32_e32 v214, 0xda24260, v214
	v_max_f32_e32 v215, 0xda24260, v215
	v_rcp_f32_e32 v214, v214
	v_rcp_f32_e32 v215, v215
	s_nop 0
	v_pk_mul_f32 v[154:155], v[214:215], v[154:155]
	v_pk_mul_f32 v[88:89], v[88:89], v[154:155]
	s_waitcnt lgkmcnt(2)
	v_lshlrev_b32_e32 v216, 16, v196
	v_and_b32_e32 v217, 0xffff0000, v196
	v_lshlrev_b32_e32 v156, 16, v192
	v_and_b32_e32 v157, 0xffff0000, v192
	v_max_f32_e32 v216, v216, v216
	v_max_f32_e32 v217, v217, v217
	v_max_f32_e32 v216, 0xda24260, v216
	v_max_f32_e32 v217, 0xda24260, v217
	v_rcp_f32_e32 v216, v216
	v_rcp_f32_e32 v217, v217
	s_nop 0
	v_pk_mul_f32 v[156:157], v[216:217], v[156:157]
	v_pk_mul_f32 v[82:83], v[82:83], v[156:157]
	s_waitcnt lgkmcnt(0)
; #define GAS __attribute__((address_space(1)))
; __device__ __forceinline__ float fast_rcp(float x) { return __builtin_amdgcn_rcpf(x); }
; __device__ __forceinline__ v4u tr4(int a, v4u x) { return (v4u){bperm(a, x.x), bperm(a, x.y), bperm(a, x.z), bperm(a, x.w)}; }
;     __device__ __forceinline__ bool operator()(AccT& acc, const Unit& u, int wr, int wc, int fr, int fq) const {
;     ...
;                     const v4u ga = tr4(t.push, *(const GAS v4u*)(Gt + r * (3 * D) + n * D + col0 + bj * 128));
;                     float f[8] = {bflo(ga.x), bfhi(ga.x), bflo(ga.y), bfhi(ga.y), bflo(ga.z), bfhi(ga.z), bflo(ga.w), bfhi(ga.w)};
;                     if (n < 2) { const v4u gb = tr4(t.push, *(const GAS v4u*)(Gt + r * (3 * D) + (n + 1) * D + col0 + bj * 128));
;                         const float h[8] = {bflo(gb.x), bfhi(gb.x), bflo(gb.y), bfhi(gb.y), bflo(gb.z), bfhi(gb.z), bflo(gb.w), bfhi(gb.w)};
; #pragma unroll
;                         for (int e = 0; e < 8; ++e) f[e] = f[e] * fast_rcp(fmaxf(h[e], 1e-30f)); }
;                     f32x4 v0 = acc[ai][bj][m][0], v1 = acc[ai][bj][m][1];
;                     v0 = v0 * (f32x4){f[0], f[1], f[2], f[3]}; v1 = v1 * (f32x4){f[4], f[5], f[6], f[7]};
;                     acc[ai][bj][m][0] = v0; acc[ai][bj][m][1] = v1;
	v_lshlrev_b32_e32 v160, 16, v197
	v_and_b32_e32 v161, 0xffff0000, v197
	v_lshlrev_b32_e32 v158, 16, v193
	v_and_b32_e32 v159, 0xffff0000, v193
	v_max_f32_e32 v160, v160, v160
	v_max_f32_e32 v161, v161, v161
	v_max_f32_e32 v160, 0xda24260, v160
	v_max_f32_e32 v161, 0xda24260, v161
	v_rcp_f32_e32 v160, v160
	v_rcp_f32_e32 v161, v161
	s_nop 0
	v_pk_mul_f32 v[158:159], v[160:161], v[158:159]
	v_pk_mul_f32 v[84:85], v[84:85], v[158:159]
	global_load_dwordx4 v[190:193], v[146:147], off offset:256
	global_load_dwordx4 v[194:197], v[146:147], off offset:2304
	s_waitcnt vmcnt(10)
	ds_bpermute_b32 v198, v165, v198
	ds_bpermute_b32 v202, v165, v202
	ds_bpermute_b32 v199, v165, v199
	ds_bpermute_b32 v203, v165, v203
	ds_bpermute_b32 v200, v165, v200
	ds_bpermute_b32 v204, v165, v204
	ds_bpermute_b32 v201, v165, v201
	ds_bpermute_b32 v205, v165, v205
	s_waitcnt lgkmcnt(6)
	v_lshlrev_b32_e32 v160, 16, v202
	v_and_b32_e32 v161, 0xffff0000, v202
	v_lshlrev_b32_e32 v150, 16, v198
	v_and_b32_e32 v151, 0xffff0000, v198
	v_max_f32_e32 v160, v160, v160
	v_max_f32_e32 v161, v161, v161
	v_max_f32_e32 v160, 0xda24260, v160
	v_max_f32_e32 v161, 0xda24260, v161
	v_rcp_f32_e32 v160, v160
	v_rcp_f32_e32 v161, v161
	s_nop 0
	v_pk_mul_f32 v[150:151], v[160:161], v[150:151]
	v_pk_mul_f32 v[110:111], v[110:111], v[150:151]
	s_waitcnt lgkmcnt(4)
	v_lshlrev_b32_e32 v214, 16, v203
	v_and_b32_e32 v215, 0xffff0000, v203
	v_lshlrev_b32_e32 v154, 16, v199
	v_and_b32_e32 v155, 0xffff0000, v199
	v_max_f32_e32 v214, v214, v214
	v_max_f32_e32 v215, v215, v215
	v_max_f32_e32 v214, 0xda24260, v214
	v_max_f32_e32 v215, 0xda24260, v215
	v_rcp_f32_e32 v214, v214
	v_rcp_f32_e32 v215, v215
	s_nop 0
	v_pk_mul_f32 v[154:155], v[214:215], v[154:155]
	v_pk_mul_f32 v[112:113], v[112:113], v[154:155]
	s_waitcnt lgkmcnt(2)
	v_lshlrev_b32_e32 v216, 16, v204
	v_and_b32_e32 v217, 0xffff0000, v204
	v_lshlrev_b32_e32 v156, 16, v200
	v_and_b32_e32 v157, 0xffff0000, v200
	v_max_f32_e32 v216, v216, v216
	v_max_f32_e32 v217, v217, v217
	v_max_f32_e32 v216, 0xda24260, v216
	v_max_f32_e32 v217, 0xda24260, v217
	v_rcp_f32_e32 v216, v216
	v_rcp_f32_e32 v217, v217
	s_nop 0
	v_pk_mul_f32 v[156:157], v[216:217], v[156:157]
	v_pk_mul_f32 v[106:107], v[106:107], v[156:157]
	s_waitcnt lgkmcnt(0)
	v_lshlrev_b32_e32 v160, 16, v205
	v_and_b32_e32 v161, 0xffff0000, v205
	v_lshlrev_b32_e32 v158, 16, v201
	v_and_b32_e32 v159, 0xffff0000, v201
	v_max_f32_e32 v160, v160, v160
	v_max_f32_e32 v161, v161, v161
	v_max_f32_e32 v160, 0xda24260, v160
	v_max_f32_e32 v161, 0xda24260, v161
	v_rcp_f32_e32 v160, v160
	v_rcp_f32_e32 v161, v161
	s_nop 0
	v_pk_mul_f32 v[158:159], v[160:161], v[158:159]
	v_pk_mul_f32 v[108:109], v[108:109], v[158:159]
	s_mov_b64 s[100:101], 0xd8000
	v_lshl_add_u64 v[146:147], v[152:153], 0, s[100:101]
	global_load_dwordx4 v[198:201], v[146:147], off
	global_load_dwordx4 v[202:205], v[146:147], off offset:2048
	s_waitcnt vmcnt(10)
	ds_bpermute_b32 v206, v165, v206
	ds_bpermute_b32 v210, v165, v210
	ds_bpermute_b32 v207, v165, v207
	ds_bpermute_b32 v211, v165, v211
	ds_bpermute_b32 v208, v165, v208
	ds_bpermute_b32 v212, v165, v212
	ds_bpermute_b32 v209, v165, v209
	ds_bpermute_b32 v213, v165, v213
	s_waitcnt lgkmcnt(6)
	v_lshlrev_b32_e32 v160, 16, v210
	v_and_b32_e32 v161, 0xffff0000, v210
	v_lshlrev_b32_e32 v150, 16, v206
	v_and_b32_e32 v151, 0xffff0000, v206
	v_max_f32_e32 v160, v160, v160
	v_max_f32_e32 v161, v161, v161
	v_max_f32_e32 v160, 0xda24260, v160
	v_max_f32_e32 v161, 0xda24260, v161
	v_rcp_f32_e32 v160, v160
	v_rcp_f32_e32 v161, v161
	s_nop 0
	v_pk_mul_f32 v[150:151], v[160:161], v[150:151]
	v_pk_mul_f32 v[78:79], v[78:79], v[150:151]
	s_waitcnt lgkmcnt(4)
	v_lshlrev_b32_e32 v214, 16, v211
	v_and_b32_e32 v215, 0xffff0000, v211
	v_lshlrev_b32_e32 v154, 16, v207
	v_and_b32_e32 v155, 0xffff0000, v207
	v_max_f32_e32 v214, v214, v214
	v_max_f32_e32 v215, v215, v215
	v_max_f32_e32 v214, 0xda24260, v214
	v_max_f32_e32 v215, 0xda24260, v215
	v_rcp_f32_e32 v214, v214
	v_rcp_f32_e32 v215, v215
	s_nop 0
	v_pk_mul_f32 v[154:155], v[214:215], v[154:155]
	v_pk_mul_f32 v[80:81], v[80:81], v[154:155]
	s_waitcnt lgkmcnt(2)
	v_lshlrev_b32_e32 v216, 16, v212
	v_and_b32_e32 v217, 0xffff0000, v212
	v_lshlrev_b32_e32 v156, 16, v208
	v_and_b32_e32 v157, 0xffff0000, v208
	v_max_f32_e32 v216, v216, v216
	v_max_f32_e32 v217, v217, v217
	v_max_f32_e32 v216, 0xda24260, v216
	v_max_f32_e32 v217, 0xda24260, v217
	v_rcp_f32_e32 v216, v216
	v_rcp_f32_e32 v217, v217
	s_nop 0
	v_pk_mul_f32 v[156:157], v[216:217], v[156:157]
	v_pk_mul_f32 v[74:75], v[74:75], v[156:157]
	s_waitcnt lgkmcnt(0)
	v_lshlrev_b32_e32 v160, 16, v213
	v_and_b32_e32 v161, 0xffff0000, v213
	v_lshlrev_b32_e32 v158, 16, v209
	v_and_b32_e32 v159, 0xffff0000, v209
	v_max_f32_e32 v160, v160, v160
	v_max_f32_e32 v161, v161, v161
	v_max_f32_e32 v160, 0xda24260, v160
	v_max_f32_e32 v161, 0xda24260, v161
	v_rcp_f32_e32 v160, v160
	v_rcp_f32_e32 v161, v161
	s_nop 0
	v_pk_mul_f32 v[158:159], v[160:161], v[158:159]
	v_pk_mul_f32 v[76:77], v[76:77], v[158:159]
	global_load_dwordx4 v[206:209], v[146:147], off offset:256
	global_load_dwordx4 v[210:213], v[146:147], off offset:2304
	s_waitcnt vmcnt(10)
	ds_bpermute_b32 v166, v165, v166
	ds_bpermute_b32 v170, v165, v170
	ds_bpermute_b32 v167, v165, v167
	ds_bpermute_b32 v171, v165, v171
	ds_bpermute_b32 v168, v165, v168
	ds_bpermute_b32 v172, v165, v172
	ds_bpermute_b32 v169, v165, v169
	ds_bpermute_b32 v173, v165, v173
	s_waitcnt lgkmcnt(6)
; #define GAS __attribute__((address_space(1)))
; __device__ __forceinline__ float fast_rcp(float x) { return __builtin_amdgcn_rcpf(x); }
; __device__ __forceinline__ v4u tr4(int a, v4u x) { return (v4u){bperm(a, x.x), bperm(a, x.y), bperm(a, x.z), bperm(a, x.w)}; }
;     __device__ __forceinline__ bool operator()(AccT& acc, const Unit& u, int wr, int wc, int fr, int fq) const {
;     ...
;                     const v4u ga = tr4(t.push, *(const GAS v4u*)(Gt + r * (3 * D) + n * D + col0 + bj * 128));
;                     float f[8] = {bflo(ga.x), bfhi(ga.x), bflo(ga.y), bfhi(ga.y), bflo(ga.z), bfhi(ga.z), bflo(ga.w), bfhi(ga.w)};
;                     if (n < 2) { const v4u gb = tr4(t.push, *(const GAS v4u*)(Gt + r * (3 * D) + (n + 1) * D + col0 + bj * 128));
;                         const float h[8] = {bflo(gb.x), bfhi(gb.x), bflo(gb.y), bfhi(gb.y), bflo(gb.z), bfhi(gb.z), bflo(gb.w), bfhi(gb.w)};
; #pragma unroll
;                         for (int e = 0; e < 8; ++e) f[e] = f[e] * fast_rcp(fmaxf(h[e], 1e-30f)); }
;                     f32x4 v0 = acc[ai][bj][m][0], v1 = acc[ai][bj][m][1];
;                     v0 = v0 * (f32x4){f[0], f[1], f[2], f[3]}; v1 = v1 * (f32x4){f[4], f[5], f[6], f[7]};
;                     acc[ai][bj][m][0] = v0; acc[ai][bj][m][1] = v1;
	v_lshlrev_b32_e32 v160, 16, v170
	v_and_b32_e32 v161, 0xffff0000, v170
	v_lshlrev_b32_e32 v150, 16, v166
	v_and_b32_e32 v151, 0xffff0000, v166
	v_max_f32_e32 v160, v160, v160
	v_max_f32_e32 v161, v161, v161
	v_max_f32_e32 v160, 0xda24260, v160
	v_max_f32_e32 v161, 0xda24260, v161
	v_rcp_f32_e32 v160, v160
	v_rcp_f32_e32 v161, v161
	s_nop 0
	v_pk_mul_f32 v[150:151], v[160:161], v[150:151]
	v_pk_mul_f32 v[102:103], v[102:103], v[150:151]
	s_waitcnt lgkmcnt(4)
	v_lshlrev_b32_e32 v214, 16, v171
	v_and_b32_e32 v215, 0xffff0000, v171
	v_lshlrev_b32_e32 v154, 16, v167
	v_and_b32_e32 v155, 0xffff0000, v167
	v_max_f32_e32 v214, v214, v214
	v_max_f32_e32 v215, v215, v215
	v_max_f32_e32 v214, 0xda24260, v214
	v_max_f32_e32 v215, 0xda24260, v215
	v_rcp_f32_e32 v214, v214
	v_rcp_f32_e32 v215, v215
	s_nop 0
	v_pk_mul_f32 v[154:155], v[214:215], v[154:155]
	v_pk_mul_f32 v[104:105], v[104:105], v[154:155]
	s_waitcnt lgkmcnt(2)
	v_lshlrev_b32_e32 v216, 16, v172
	v_and_b32_e32 v217, 0xffff0000, v172
	v_lshlrev_b32_e32 v156, 16, v168
	v_and_b32_e32 v157, 0xffff0000, v168
	v_max_f32_e32 v216, v216, v216
	v_max_f32_e32 v217, v217, v217
	v_max_f32_e32 v216, 0xda24260, v216
	v_max_f32_e32 v217, 0xda24260, v217
	v_rcp_f32_e32 v216, v216
	v_rcp_f32_e32 v217, v217
	s_nop 0
	v_pk_mul_f32 v[156:157], v[216:217], v[156:157]
	v_pk_mul_f32 v[98:99], v[98:99], v[156:157]
	s_waitcnt lgkmcnt(0)
	v_lshlrev_b32_e32 v160, 16, v173
	v_and_b32_e32 v161, 0xffff0000, v173
	v_lshlrev_b32_e32 v158, 16, v169
	v_and_b32_e32 v159, 0xffff0000, v169
	v_max_f32_e32 v160, v160, v160
	v_max_f32_e32 v161, v161, v161
	v_max_f32_e32 v160, 0xda24260, v160
	v_max_f32_e32 v161, 0xda24260, v161
	v_rcp_f32_e32 v160, v160
	v_rcp_f32_e32 v161, v161
	s_nop 0
	v_pk_mul_f32 v[158:159], v[160:161], v[158:159]
	v_pk_mul_f32 v[100:101], v[100:101], v[158:159]
	s_mov_b64 s[100:101], 0xf0000
	v_lshl_add_u64 v[146:147], v[152:153], 0, s[100:101]
	global_load_dwordx4 v[166:169], v[146:147], off
	global_load_dwordx4 v[170:173], v[146:147], off offset:2048
	s_waitcnt vmcnt(10)
	ds_bpermute_b32 v174, v165, v174
	ds_bpermute_b32 v178, v165, v178
	ds_bpermute_b32 v175, v165, v175
	ds_bpermute_b32 v179, v165, v179
	ds_bpermute_b32 v176, v165, v176
	ds_bpermute_b32 v180, v165, v180
	ds_bpermute_b32 v177, v165, v177
	ds_bpermute_b32 v181, v165, v181
	s_waitcnt lgkmcnt(6)
	v_lshlrev_b32_e32 v160, 16, v178
	v_and_b32_e32 v161, 0xffff0000, v178
	v_lshlrev_b32_e32 v150, 16, v174
	v_and_b32_e32 v151, 0xffff0000, v174
	v_max_f32_e32 v160, v160, v160
	v_max_f32_e32 v161, v161, v161
	v_max_f32_e32 v160, 0xda24260, v160
	v_max_f32_e32 v161, 0xda24260, v161
	v_rcp_f32_e32 v160, v160
	v_rcp_f32_e32 v161, v161
	s_nop 0
	v_pk_mul_f32 v[150:151], v[160:161], v[150:151]
	v_pk_mul_f32 v[70:71], v[70:71], v[150:151]
	s_waitcnt lgkmcnt(4)
	v_lshlrev_b32_e32 v214, 16, v179
	v_and_b32_e32 v215, 0xffff0000, v179
	v_lshlrev_b32_e32 v154, 16, v175
	v_and_b32_e32 v155, 0xffff0000, v175
	v_max_f32_e32 v214, v214, v214
	v_max_f32_e32 v215, v215, v215
	v_max_f32_e32 v214, 0xda24260, v214
	v_max_f32_e32 v215, 0xda24260, v215
	v_rcp_f32_e32 v214, v214
	v_rcp_f32_e32 v215, v215
	s_nop 0
	v_pk_mul_f32 v[154:155], v[214:215], v[154:155]
	v_pk_mul_f32 v[72:73], v[72:73], v[154:155]
	s_waitcnt lgkmcnt(2)
	v_lshlrev_b32_e32 v216, 16, v180
	v_and_b32_e32 v217, 0xffff0000, v180
	v_lshlrev_b32_e32 v156, 16, v176
	v_and_b32_e32 v157, 0xffff0000, v176
	v_max_f32_e32 v216, v216, v216
	v_max_f32_e32 v217, v217, v217
	v_max_f32_e32 v216, 0xda24260, v216
	v_max_f32_e32 v217, 0xda24260, v217
	v_rcp_f32_e32 v216, v216
	v_rcp_f32_e32 v217, v217
	s_nop 0
	v_pk_mul_f32 v[156:157], v[216:217], v[156:157]
	v_pk_mul_f32 v[66:67], v[66:67], v[156:157]
	s_waitcnt lgkmcnt(0)
	v_lshlrev_b32_e32 v160, 16, v181
	v_and_b32_e32 v161, 0xffff0000, v181
	v_lshlrev_b32_e32 v158, 16, v177
	v_and_b32_e32 v159, 0xffff0000, v177
	v_max_f32_e32 v160, v160, v160
	v_max_f32_e32 v161, v161, v161
	v_max_f32_e32 v160, 0xda24260, v160
	v_max_f32_e32 v161, 0xda24260, v161
	v_rcp_f32_e32 v160, v160
	v_rcp_f32_e32 v161, v161
	s_nop 0
	v_pk_mul_f32 v[158:159], v[160:161], v[158:159]
	v_pk_mul_f32 v[68:69], v[68:69], v[158:159]
	global_load_dwordx4 v[174:177], v[146:147], off offset:256
	global_load_dwordx4 v[178:181], v[146:147], off offset:2304
	s_waitcnt vmcnt(10)
	ds_bpermute_b32 v182, v165, v182
	ds_bpermute_b32 v186, v165, v186
	ds_bpermute_b32 v183, v165, v183
	ds_bpermute_b32 v187, v165, v187
	ds_bpermute_b32 v184, v165, v184
	ds_bpermute_b32 v188, v165, v188
	ds_bpermute_b32 v185, v165, v185
	ds_bpermute_b32 v189, v165, v189
	s_waitcnt lgkmcnt(6)
	v_lshlrev_b32_e32 v160, 16, v186
	v_and_b32_e32 v161, 0xffff0000, v186
	v_lshlrev_b32_e32 v150, 16, v182
	v_and_b32_e32 v151, 0xffff0000, v182
	v_max_f32_e32 v160, v160, v160
	v_max_f32_e32 v161, v161, v161
	v_max_f32_e32 v160, 0xda24260, v160
	v_max_f32_e32 v161, 0xda24260, v161
	v_rcp_f32_e32 v160, v160
	v_rcp_f32_e32 v161, v161
	s_nop 0
	v_pk_mul_f32 v[150:151], v[160:161], v[150:151]
	v_pk_mul_f32 v[62:63], v[62:63], v[150:151]
	s_waitcnt lgkmcnt(4)
	v_lshlrev_b32_e32 v214, 16, v187
	v_and_b32_e32 v215, 0xffff0000, v187
	v_lshlrev_b32_e32 v154, 16, v183
	v_and_b32_e32 v155, 0xffff0000, v183
	v_max_f32_e32 v214, v214, v214
	v_max_f32_e32 v215, v215, v215
	v_max_f32_e32 v214, 0xda24260, v214
	v_max_f32_e32 v215, 0xda24260, v215
	v_rcp_f32_e32 v214, v214
	v_rcp_f32_e32 v215, v215
	s_nop 0
	v_pk_mul_f32 v[154:155], v[214:215], v[154:155]
	v_pk_mul_f32 v[64:65], v[64:65], v[154:155]
	s_waitcnt lgkmcnt(2)
; #define GAS __attribute__((address_space(1)))
; __device__ __forceinline__ float fast_rcp(float x) { return __builtin_amdgcn_rcpf(x); }
; __device__ __forceinline__ v4u tr4(int a, v4u x) { return (v4u){bperm(a, x.x), bperm(a, x.y), bperm(a, x.z), bperm(a, x.w)}; }
;     __device__ __forceinline__ bool operator()(AccT& acc, const Unit& u, int wr, int wc, int fr, int fq) const {
;     ...
;                     const v4u ga = tr4(t.push, *(const GAS v4u*)(Gt + r * (3 * D) + n * D + col0 + bj * 128));
;                     float f[8] = {bflo(ga.x), bfhi(ga.x), bflo(ga.y), bfhi(ga.y), bflo(ga.z), bfhi(ga.z), bflo(ga.w), bfhi(ga.w)};
;                     if (n < 2) { const v4u gb = tr4(t.push, *(const GAS v4u*)(Gt + r * (3 * D) + (n + 1) * D + col0 + bj * 128));
;                         const float h[8] = {bflo(gb.x), bfhi(gb.x), bflo(gb.y), bfhi(gb.y), bflo(gb.z), bfhi(gb.z), bflo(gb.w), bfhi(gb.w)};
; #pragma unroll
;                         for (int e = 0; e < 8; ++e) f[e] = f[e] * fast_rcp(fmaxf(h[e], 1e-30f)); }
;                     f32x4 v0 = acc[ai][bj][m][0], v1 = acc[ai][bj][m][1];
;                     v0 = v0 * (f32x4){f[0], f[1], f[2], f[3]}; v1 = v1 * (f32x4){f[4], f[5], f[6], f[7]};
;                     acc[ai][bj][m][0] = v0; acc[ai][bj][m][1] = v1;
	v_lshlrev_b32_e32 v216, 16, v188
	v_and_b32_e32 v217, 0xffff0000, v188
	v_lshlrev_b32_e32 v156, 16, v184
	v_and_b32_e32 v157, 0xffff0000, v184
	v_max_f32_e32 v216, v216, v216
	v_max_f32_e32 v217, v217, v217
	v_max_f32_e32 v216, 0xda24260, v216
	v_max_f32_e32 v217, 0xda24260, v217
	v_rcp_f32_e32 v216, v216
	v_rcp_f32_e32 v217, v217
	s_nop 0
	v_pk_mul_f32 v[156:157], v[216:217], v[156:157]
	v_pk_mul_f32 v[58:59], v[58:59], v[156:157]
	s_waitcnt lgkmcnt(0)
	v_lshlrev_b32_e32 v160, 16, v189
	v_and_b32_e32 v161, 0xffff0000, v189
	v_lshlrev_b32_e32 v158, 16, v185
	v_and_b32_e32 v159, 0xffff0000, v185
	v_max_f32_e32 v160, v160, v160
	v_max_f32_e32 v161, v161, v161
	v_max_f32_e32 v160, 0xda24260, v160
	v_max_f32_e32 v161, 0xda24260, v161
	v_rcp_f32_e32 v160, v160
	v_rcp_f32_e32 v161, v161
	s_nop 0
	v_pk_mul_f32 v[158:159], v[160:161], v[158:159]
	v_pk_mul_f32 v[60:61], v[60:61], v[158:159]
	s_mov_b64 s[100:101], 0x108000
	v_lshl_add_u64 v[146:147], v[152:153], 0, s[100:101]
	global_load_dwordx4 v[182:185], v[146:147], off
	global_load_dwordx4 v[186:189], v[146:147], off offset:2048
	s_waitcnt vmcnt(10)
	ds_bpermute_b32 v190, v165, v190
	ds_bpermute_b32 v194, v165, v194
	ds_bpermute_b32 v191, v165, v191
	ds_bpermute_b32 v195, v165, v195
	ds_bpermute_b32 v192, v165, v192
	ds_bpermute_b32 v196, v165, v196
	ds_bpermute_b32 v193, v165, v193
	ds_bpermute_b32 v197, v165, v197
	s_waitcnt lgkmcnt(6)
	v_lshlrev_b32_e32 v160, 16, v194
	v_and_b32_e32 v161, 0xffff0000, v194
	v_lshlrev_b32_e32 v150, 16, v190
	v_and_b32_e32 v151, 0xffff0000, v190
	v_max_f32_e32 v160, v160, v160
	v_max_f32_e32 v161, v161, v161
	v_max_f32_e32 v160, 0xda24260, v160
	v_max_f32_e32 v161, 0xda24260, v161
	v_rcp_f32_e32 v160, v160
	v_rcp_f32_e32 v161, v161
	s_nop 0
	v_pk_mul_f32 v[150:151], v[160:161], v[150:151]
	v_pk_mul_f32 v[30:31], v[30:31], v[150:151]
	s_waitcnt lgkmcnt(4)
	v_lshlrev_b32_e32 v214, 16, v195
	v_and_b32_e32 v215, 0xffff0000, v195
	v_lshlrev_b32_e32 v154, 16, v191
	v_and_b32_e32 v155, 0xffff0000, v191
	v_max_f32_e32 v214, v214, v214
	v_max_f32_e32 v215, v215, v215
	v_max_f32_e32 v214, 0xda24260, v214
	v_max_f32_e32 v215, 0xda24260, v215
	v_rcp_f32_e32 v214, v214
	v_rcp_f32_e32 v215, v215
	s_nop 0
	v_pk_mul_f32 v[154:155], v[214:215], v[154:155]
	v_pk_mul_f32 v[32:33], v[32:33], v[154:155]
	s_waitcnt lgkmcnt(2)
	v_lshlrev_b32_e32 v216, 16, v196
	v_and_b32_e32 v217, 0xffff0000, v196
	v_lshlrev_b32_e32 v156, 16, v192
	v_and_b32_e32 v157, 0xffff0000, v192
	v_max_f32_e32 v216, v216, v216
	v_max_f32_e32 v217, v217, v217
	v_max_f32_e32 v216, 0xda24260, v216
	v_max_f32_e32 v217, 0xda24260, v217
	v_rcp_f32_e32 v216, v216
	v_rcp_f32_e32 v217, v217
	s_nop 0
	v_pk_mul_f32 v[156:157], v[216:217], v[156:157]
	v_pk_mul_f32 v[26:27], v[26:27], v[156:157]
	s_waitcnt lgkmcnt(0)
	v_lshlrev_b32_e32 v160, 16, v197
	v_and_b32_e32 v161, 0xffff0000, v197
	v_lshlrev_b32_e32 v158, 16, v193
	v_and_b32_e32 v159, 0xffff0000, v193
	v_max_f32_e32 v160, v160, v160
	v_max_f32_e32 v161, v161, v161
	v_max_f32_e32 v160, 0xda24260, v160
	v_max_f32_e32 v161, 0xda24260, v161
	v_rcp_f32_e32 v160, v160
	v_rcp_f32_e32 v161, v161
	s_nop 0
	v_pk_mul_f32 v[158:159], v[160:161], v[158:159]
	v_pk_mul_f32 v[28:29], v[28:29], v[158:159]
	global_load_dwordx4 v[190:193], v[146:147], off offset:256
	global_load_dwordx4 v[194:197], v[146:147], off offset:2304
	s_waitcnt vmcnt(10)
	ds_bpermute_b32 v198, v165, v198
	ds_bpermute_b32 v202, v165, v202
	ds_bpermute_b32 v199, v165, v199
	ds_bpermute_b32 v203, v165, v203
	ds_bpermute_b32 v200, v165, v200
	ds_bpermute_b32 v204, v165, v204
	ds_bpermute_b32 v201, v165, v201
	ds_bpermute_b32 v205, v165, v205
	s_waitcnt lgkmcnt(6)
	v_lshlrev_b32_e32 v160, 16, v202
	v_and_b32_e32 v161, 0xffff0000, v202
	v_lshlrev_b32_e32 v150, 16, v198
	v_and_b32_e32 v151, 0xffff0000, v198
	v_max_f32_e32 v160, v160, v160
	v_max_f32_e32 v161, v161, v161
	v_max_f32_e32 v160, 0xda24260, v160
	v_max_f32_e32 v161, 0xda24260, v161
	v_rcp_f32_e32 v160, v160
	v_rcp_f32_e32 v161, v161
	s_nop 0
	v_pk_mul_f32 v[150:151], v[160:161], v[150:151]
	v_pk_mul_f32 v[54:55], v[54:55], v[150:151]
	s_waitcnt lgkmcnt(4)
	v_lshlrev_b32_e32 v214, 16, v203
	v_and_b32_e32 v215, 0xffff0000, v203
	v_lshlrev_b32_e32 v154, 16, v199
	v_and_b32_e32 v155, 0xffff0000, v199
	v_max_f32_e32 v214, v214, v214
	v_max_f32_e32 v215, v215, v215
	v_max_f32_e32 v214, 0xda24260, v214
	v_max_f32_e32 v215, 0xda24260, v215
	v_rcp_f32_e32 v214, v214
	v_rcp_f32_e32 v215, v215
	s_nop 0
	v_pk_mul_f32 v[154:155], v[214:215], v[154:155]
	v_pk_mul_f32 v[56:57], v[56:57], v[154:155]
	s_waitcnt lgkmcnt(2)
	v_lshlrev_b32_e32 v216, 16, v204
	v_and_b32_e32 v217, 0xffff0000, v204
	v_lshlrev_b32_e32 v156, 16, v200
	v_and_b32_e32 v157, 0xffff0000, v200
	v_max_f32_e32 v216, v216, v216
	v_max_f32_e32 v217, v217, v217
	v_max_f32_e32 v216, 0xda24260, v216
	v_max_f32_e32 v217, 0xda24260, v217
	v_rcp_f32_e32 v216, v216
	v_rcp_f32_e32 v217, v217
	s_nop 0
	v_pk_mul_f32 v[156:157], v[216:217], v[156:157]
	v_pk_mul_f32 v[50:51], v[50:51], v[156:157]
	s_waitcnt lgkmcnt(0)
	v_lshlrev_b32_e32 v160, 16, v205
	v_and_b32_e32 v161, 0xffff0000, v205
	v_lshlrev_b32_e32 v158, 16, v201
	v_and_b32_e32 v159, 0xffff0000, v201
	v_max_f32_e32 v160, v160, v160
	v_max_f32_e32 v161, v161, v161
	v_max_f32_e32 v160, 0xda24260, v160
	v_max_f32_e32 v161, 0xda24260, v161
	v_rcp_f32_e32 v160, v160
	v_rcp_f32_e32 v161, v161
	s_nop 0
	v_pk_mul_f32 v[158:159], v[160:161], v[158:159]
	v_pk_mul_f32 v[52:53], v[52:53], v[158:159]
	s_waitcnt vmcnt(8)
	ds_bpermute_b32 v206, v165, v206
	ds_bpermute_b32 v210, v165, v210
	ds_bpermute_b32 v207, v165, v207
	ds_bpermute_b32 v211, v165, v211
	ds_bpermute_b32 v208, v165, v208
	ds_bpermute_b32 v212, v165, v212
	ds_bpermute_b32 v209, v165, v209
	ds_bpermute_b32 v213, v165, v213
	s_waitcnt lgkmcnt(6)
; #define GAS __attribute__((address_space(1)))
; __device__ __forceinline__ float fast_rcp(float x) { return __builtin_amdgcn_rcpf(x); }
; __device__ __forceinline__ v4u tr4(int a, v4u x) { return (v4u){bperm(a, x.x), bperm(a, x.y), bperm(a, x.z), bperm(a, x.w)}; }
;     __device__ __forceinline__ bool operator()(AccT& acc, const Unit& u, int wr, int wc, int fr, int fq) const {
;     ...
;                     const v4u ga = tr4(t.push, *(const GAS v4u*)(Gt + r * (3 * D) + n * D + col0 + bj * 128));
;                     float f[8] = {bflo(ga.x), bfhi(ga.x), bflo(ga.y), bfhi(ga.y), bflo(ga.z), bfhi(ga.z), bflo(ga.w), bfhi(ga.w)};
;                     if (n < 2) { const v4u gb = tr4(t.push, *(const GAS v4u*)(Gt + r * (3 * D) + (n + 1) * D + col0 + bj * 128));
;                         const float h[8] = {bflo(gb.x), bfhi(gb.x), bflo(gb.y), bfhi(gb.y), bflo(gb.z), bfhi(gb.z), bflo(gb.w), bfhi(gb.w)};
; #pragma unroll
;                         for (int e = 0; e < 8; ++e) f[e] = f[e] * fast_rcp(fmaxf(h[e], 1e-30f)); }
;                     f32x4 v0 = acc[ai][bj][m][0], v1 = acc[ai][bj][m][1];
;                     v0 = v0 * (f32x4){f[0], f[1], f[2], f[3]}; v1 = v1 * (f32x4){f[4], f[5], f[6], f[7]};
;                     acc[ai][bj][m][0] = v0; acc[ai][bj][m][1] = v1;
	v_lshlrev_b32_e32 v160, 16, v210
	v_and_b32_e32 v161, 0xffff0000, v210
	v_lshlrev_b32_e32 v150, 16, v206
	v_and_b32_e32 v151, 0xffff0000, v206
	v_max_f32_e32 v160, v160, v160
	v_max_f32_e32 v161, v161, v161
	v_max_f32_e32 v160, 0xda24260, v160
	v_max_f32_e32 v161, 0xda24260, v161
	v_rcp_f32_e32 v160, v160
	v_rcp_f32_e32 v161, v161
	s_nop 0
	v_pk_mul_f32 v[150:151], v[160:161], v[150:151]
	v_pk_mul_f32 v[22:23], v[22:23], v[150:151]
	s_waitcnt lgkmcnt(4)
	v_lshlrev_b32_e32 v214, 16, v211
	v_and_b32_e32 v215, 0xffff0000, v211
	v_lshlrev_b32_e32 v154, 16, v207
	v_and_b32_e32 v155, 0xffff0000, v207
	v_max_f32_e32 v214, v214, v214
	v_max_f32_e32 v215, v215, v215
	v_max_f32_e32 v214, 0xda24260, v214
	v_max_f32_e32 v215, 0xda24260, v215
	v_rcp_f32_e32 v214, v214
	v_rcp_f32_e32 v215, v215
	s_nop 0
	v_pk_mul_f32 v[154:155], v[214:215], v[154:155]
	v_pk_mul_f32 v[24:25], v[24:25], v[154:155]
	s_waitcnt lgkmcnt(2)
	v_lshlrev_b32_e32 v216, 16, v212
	v_and_b32_e32 v217, 0xffff0000, v212
	v_lshlrev_b32_e32 v156, 16, v208
	v_and_b32_e32 v157, 0xffff0000, v208
	v_max_f32_e32 v216, v216, v216
	v_max_f32_e32 v217, v217, v217
	v_max_f32_e32 v216, 0xda24260, v216
	v_max_f32_e32 v217, 0xda24260, v217
	v_rcp_f32_e32 v216, v216
	v_rcp_f32_e32 v217, v217
	s_nop 0
	v_pk_mul_f32 v[156:157], v[216:217], v[156:157]
	v_pk_mul_f32 v[18:19], v[18:19], v[156:157]
	s_waitcnt lgkmcnt(0)
	v_lshlrev_b32_e32 v160, 16, v213
	v_and_b32_e32 v161, 0xffff0000, v213
	v_lshlrev_b32_e32 v158, 16, v209
	v_and_b32_e32 v159, 0xffff0000, v209
	v_max_f32_e32 v160, v160, v160
	v_max_f32_e32 v161, v161, v161
	v_max_f32_e32 v160, 0xda24260, v160
	v_max_f32_e32 v161, 0xda24260, v161
	v_rcp_f32_e32 v160, v160
	v_rcp_f32_e32 v161, v161
	s_nop 0
	v_pk_mul_f32 v[158:159], v[160:161], v[158:159]
	v_pk_mul_f32 v[20:21], v[20:21], v[158:159]
	s_waitcnt vmcnt(6)
	ds_bpermute_b32 v166, v165, v166
	ds_bpermute_b32 v170, v165, v170
	ds_bpermute_b32 v167, v165, v167
	ds_bpermute_b32 v171, v165, v171
	ds_bpermute_b32 v168, v165, v168
	ds_bpermute_b32 v172, v165, v172
	ds_bpermute_b32 v169, v165, v169
	ds_bpermute_b32 v173, v165, v173
	s_waitcnt lgkmcnt(6)
	v_lshlrev_b32_e32 v160, 16, v170
	v_and_b32_e32 v161, 0xffff0000, v170
	v_lshlrev_b32_e32 v150, 16, v166
	v_and_b32_e32 v151, 0xffff0000, v166
	v_max_f32_e32 v160, v160, v160
	v_max_f32_e32 v161, v161, v161
	v_max_f32_e32 v160, 0xda24260, v160
	v_max_f32_e32 v161, 0xda24260, v161
	v_rcp_f32_e32 v160, v160
	v_rcp_f32_e32 v161, v161
	s_nop 0
	v_pk_mul_f32 v[150:151], v[160:161], v[150:151]
	v_pk_mul_f32 v[46:47], v[46:47], v[150:151]
	s_waitcnt lgkmcnt(4)
	v_lshlrev_b32_e32 v214, 16, v171
	v_and_b32_e32 v215, 0xffff0000, v171
	v_lshlrev_b32_e32 v154, 16, v167
	v_and_b32_e32 v155, 0xffff0000, v167
	v_max_f32_e32 v214, v214, v214
	v_max_f32_e32 v215, v215, v215
	v_max_f32_e32 v214, 0xda24260, v214
	v_max_f32_e32 v215, 0xda24260, v215
	v_rcp_f32_e32 v214, v214
	v_rcp_f32_e32 v215, v215
	s_nop 0
	v_pk_mul_f32 v[154:155], v[214:215], v[154:155]
	v_pk_mul_f32 v[48:49], v[48:49], v[154:155]
	s_waitcnt lgkmcnt(2)
	v_lshlrev_b32_e32 v216, 16, v172
	v_and_b32_e32 v217, 0xffff0000, v172
	v_lshlrev_b32_e32 v156, 16, v168
	v_and_b32_e32 v157, 0xffff0000, v168
	v_max_f32_e32 v216, v216, v216
	v_max_f32_e32 v217, v217, v217
	v_max_f32_e32 v216, 0xda24260, v216
	v_max_f32_e32 v217, 0xda24260, v217
	v_rcp_f32_e32 v216, v216
	v_rcp_f32_e32 v217, v217
	s_nop 0
	v_pk_mul_f32 v[156:157], v[216:217], v[156:157]
	v_pk_mul_f32 v[42:43], v[42:43], v[156:157]
	s_waitcnt lgkmcnt(0)
	v_lshlrev_b32_e32 v160, 16, v173
	v_and_b32_e32 v161, 0xffff0000, v173
	v_lshlrev_b32_e32 v158, 16, v169
	v_and_b32_e32 v159, 0xffff0000, v169
	v_max_f32_e32 v160, v160, v160
	v_max_f32_e32 v161, v161, v161
	v_max_f32_e32 v160, 0xda24260, v160
	v_max_f32_e32 v161, 0xda24260, v161
	v_rcp_f32_e32 v160, v160
	v_rcp_f32_e32 v161, v161
	s_nop 0
	v_pk_mul_f32 v[158:159], v[160:161], v[158:159]
	v_pk_mul_f32 v[44:45], v[44:45], v[158:159]
	s_waitcnt vmcnt(4)
	ds_bpermute_b32 v174, v165, v174
	ds_bpermute_b32 v178, v165, v178
	ds_bpermute_b32 v175, v165, v175
	ds_bpermute_b32 v179, v165, v179
	ds_bpermute_b32 v176, v165, v176
	ds_bpermute_b32 v180, v165, v180
	ds_bpermute_b32 v177, v165, v177
	ds_bpermute_b32 v181, v165, v181
	s_waitcnt lgkmcnt(6)
	v_lshlrev_b32_e32 v160, 16, v178
	v_and_b32_e32 v161, 0xffff0000, v178
	v_lshlrev_b32_e32 v150, 16, v174
	v_and_b32_e32 v151, 0xffff0000, v174
	v_max_f32_e32 v160, v160, v160
	v_max_f32_e32 v161, v161, v161
	v_max_f32_e32 v160, 0xda24260, v160
	v_max_f32_e32 v161, 0xda24260, v161
	v_rcp_f32_e32 v160, v160
	v_rcp_f32_e32 v161, v161
	s_nop 0
	v_pk_mul_f32 v[150:151], v[160:161], v[150:151]
	v_pk_mul_f32 v[14:15], v[14:15], v[150:151]
	s_waitcnt lgkmcnt(4)
	v_lshlrev_b32_e32 v214, 16, v179
	v_and_b32_e32 v215, 0xffff0000, v179
	v_lshlrev_b32_e32 v154, 16, v175
	v_and_b32_e32 v155, 0xffff0000, v175
	v_max_f32_e32 v214, v214, v214
	v_max_f32_e32 v215, v215, v215
	v_max_f32_e32 v214, 0xda24260, v214
	v_max_f32_e32 v215, 0xda24260, v215
	v_rcp_f32_e32 v214, v214
	v_rcp_f32_e32 v215, v215
	s_nop 0
	v_pk_mul_f32 v[154:155], v[214:215], v[154:155]
	v_pk_mul_f32 v[16:17], v[16:17], v[154:155]
	s_waitcnt lgkmcnt(2)
	v_lshlrev_b32_e32 v216, 16, v180
	v_and_b32_e32 v217, 0xffff0000, v180
	v_lshlrev_b32_e32 v156, 16, v176
	v_and_b32_e32 v157, 0xffff0000, v176
	v_max_f32_e32 v216, v216, v216
	v_max_f32_e32 v217, v217, v217
	v_max_f32_e32 v216, 0xda24260, v216
	v_max_f32_e32 v217, 0xda24260, v217
	v_rcp_f32_e32 v216, v216
	v_rcp_f32_e32 v217, v217
	s_nop 0
	v_pk_mul_f32 v[156:157], v[216:217], v[156:157]
	v_pk_mul_f32 v[10:11], v[10:11], v[156:157]
	s_waitcnt lgkmcnt(0)
; #define GAS __attribute__((address_space(1)))
; __device__ __forceinline__ float fast_rcp(float x) { return __builtin_amdgcn_rcpf(x); }
; __device__ __forceinline__ v4u tr4(int a, v4u x) { return (v4u){bperm(a, x.x), bperm(a, x.y), bperm(a, x.z), bperm(a, x.w)}; }
;     __device__ __forceinline__ bool operator()(AccT& acc, const Unit& u, int wr, int wc, int fr, int fq) const {
;     ...
;                     const v4u ga = tr4(t.push, *(const GAS v4u*)(Gt + r * (3 * D) + n * D + col0 + bj * 128));
;                     float f[8] = {bflo(ga.x), bfhi(ga.x), bflo(ga.y), bfhi(ga.y), bflo(ga.z), bfhi(ga.z), bflo(ga.w), bfhi(ga.w)};
;                     if (n < 2) { const v4u gb = tr4(t.push, *(const GAS v4u*)(Gt + r * (3 * D) + (n + 1) * D + col0 + bj * 128));
;                         const float h[8] = {bflo(gb.x), bfhi(gb.x), bflo(gb.y), bfhi(gb.y), bflo(gb.z), bfhi(gb.z), bflo(gb.w), bfhi(gb.w)};
; #pragma unroll
;                         for (int e = 0; e < 8; ++e) f[e] = f[e] * fast_rcp(fmaxf(h[e], 1e-30f)); }
;                     f32x4 v0 = acc[ai][bj][m][0], v1 = acc[ai][bj][m][1];
;                     v0 = v0 * (f32x4){f[0], f[1], f[2], f[3]}; v1 = v1 * (f32x4){f[4], f[5], f[6], f[7]};
;                     acc[ai][bj][m][0] = v0; acc[ai][bj][m][1] = v1;
	v_lshlrev_b32_e32 v160, 16, v181
	v_and_b32_e32 v161, 0xffff0000, v181
	v_lshlrev_b32_e32 v158, 16, v177
	v_and_b32_e32 v159, 0xffff0000, v177
	v_max_f32_e32 v160, v160, v160
	v_max_f32_e32 v161, v161, v161
	v_max_f32_e32 v160, 0xda24260, v160
	v_max_f32_e32 v161, 0xda24260, v161
	v_rcp_f32_e32 v160, v160
	v_rcp_f32_e32 v161, v161
	s_nop 0
	v_pk_mul_f32 v[158:159], v[160:161], v[158:159]
	v_pk_mul_f32 v[12:13], v[12:13], v[158:159]
	s_waitcnt vmcnt(2)
	ds_bpermute_b32 v182, v165, v182
	ds_bpermute_b32 v186, v165, v186
	ds_bpermute_b32 v183, v165, v183
	ds_bpermute_b32 v187, v165, v187
	ds_bpermute_b32 v184, v165, v184
	ds_bpermute_b32 v188, v165, v188
	ds_bpermute_b32 v185, v165, v185
	ds_bpermute_b32 v189, v165, v189
	s_waitcnt lgkmcnt(6)
	v_lshlrev_b32_e32 v160, 16, v186
	v_and_b32_e32 v161, 0xffff0000, v186
	v_lshlrev_b32_e32 v150, 16, v182
	v_and_b32_e32 v151, 0xffff0000, v182
	v_max_f32_e32 v160, v160, v160
	v_max_f32_e32 v161, v161, v161
	v_max_f32_e32 v160, 0xda24260, v160
	v_max_f32_e32 v161, 0xda24260, v161
	v_rcp_f32_e32 v160, v160
	v_rcp_f32_e32 v161, v161
	s_nop 0
	v_pk_mul_f32 v[150:151], v[160:161], v[150:151]
	v_pk_mul_f32 v[38:39], v[38:39], v[150:151]
	s_waitcnt lgkmcnt(4)
	v_lshlrev_b32_e32 v214, 16, v187
	v_and_b32_e32 v215, 0xffff0000, v187
	v_lshlrev_b32_e32 v154, 16, v183
	v_and_b32_e32 v155, 0xffff0000, v183
	v_max_f32_e32 v214, v214, v214
	v_max_f32_e32 v215, v215, v215
	v_max_f32_e32 v214, 0xda24260, v214
	v_max_f32_e32 v215, 0xda24260, v215
	v_rcp_f32_e32 v214, v214
	v_rcp_f32_e32 v215, v215
	s_nop 0
	v_pk_mul_f32 v[154:155], v[214:215], v[154:155]
	v_pk_mul_f32 v[40:41], v[40:41], v[154:155]
	s_waitcnt lgkmcnt(2)
	v_lshlrev_b32_e32 v216, 16, v188
	v_and_b32_e32 v217, 0xffff0000, v188
	v_lshlrev_b32_e32 v156, 16, v184
	v_and_b32_e32 v157, 0xffff0000, v184
	v_max_f32_e32 v216, v216, v216
	v_max_f32_e32 v217, v217, v217
	v_max_f32_e32 v216, 0xda24260, v216
	v_max_f32_e32 v217, 0xda24260, v217
	v_rcp_f32_e32 v216, v216
	v_rcp_f32_e32 v217, v217
	s_nop 0
	v_pk_mul_f32 v[156:157], v[216:217], v[156:157]
	v_pk_mul_f32 v[34:35], v[34:35], v[156:157]
	s_waitcnt lgkmcnt(0)
	v_lshlrev_b32_e32 v160, 16, v189
	v_and_b32_e32 v161, 0xffff0000, v189
	v_lshlrev_b32_e32 v158, 16, v185
	v_and_b32_e32 v159, 0xffff0000, v185
	v_max_f32_e32 v160, v160, v160
	v_max_f32_e32 v161, v161, v161
	v_max_f32_e32 v160, 0xda24260, v160
	v_max_f32_e32 v161, 0xda24260, v161
	v_rcp_f32_e32 v160, v160
	v_rcp_f32_e32 v161, v161
	s_nop 0
	v_pk_mul_f32 v[158:159], v[160:161], v[158:159]
	v_pk_mul_f32 v[36:37], v[36:37], v[158:159]
	s_waitcnt vmcnt(0)
	ds_bpermute_b32 v190, v165, v190
	ds_bpermute_b32 v194, v165, v194
	ds_bpermute_b32 v191, v165, v191
	ds_bpermute_b32 v195, v165, v195
	ds_bpermute_b32 v192, v165, v192
	ds_bpermute_b32 v196, v165, v196
	ds_bpermute_b32 v193, v165, v193
	ds_bpermute_b32 v197, v165, v197
	s_waitcnt lgkmcnt(6)
	v_lshlrev_b32_e32 v160, 16, v194
	v_and_b32_e32 v161, 0xffff0000, v194
	v_lshlrev_b32_e32 v150, 16, v190
	v_and_b32_e32 v151, 0xffff0000, v190
	v_max_f32_e32 v160, v160, v160
	v_max_f32_e32 v161, v161, v161
	v_max_f32_e32 v160, 0xda24260, v160
	v_max_f32_e32 v161, 0xda24260, v161
	v_rcp_f32_e32 v160, v160
	v_rcp_f32_e32 v161, v161
	s_nop 0
	v_pk_mul_f32 v[150:151], v[160:161], v[150:151]
	v_pk_mul_f32 v[6:7], v[6:7], v[150:151]
	s_waitcnt lgkmcnt(4)
	v_lshlrev_b32_e32 v214, 16, v195
	v_and_b32_e32 v215, 0xffff0000, v195
	v_lshlrev_b32_e32 v154, 16, v191
	v_and_b32_e32 v155, 0xffff0000, v191
	v_max_f32_e32 v214, v214, v214
	v_max_f32_e32 v215, v215, v215
	v_max_f32_e32 v214, 0xda24260, v214
	v_max_f32_e32 v215, 0xda24260, v215
	v_rcp_f32_e32 v214, v214
	v_rcp_f32_e32 v215, v215
	s_nop 0
	v_pk_mul_f32 v[154:155], v[214:215], v[154:155]
	v_pk_mul_f32 v[8:9], v[8:9], v[154:155]
	s_waitcnt lgkmcnt(2)
	v_lshlrev_b32_e32 v216, 16, v196
	v_and_b32_e32 v217, 0xffff0000, v196
	v_lshlrev_b32_e32 v156, 16, v192
	v_and_b32_e32 v157, 0xffff0000, v192
	v_max_f32_e32 v216, v216, v216
	v_max_f32_e32 v217, v217, v217
	v_max_f32_e32 v216, 0xda24260, v216
	v_max_f32_e32 v217, 0xda24260, v217
	v_rcp_f32_e32 v216, v216
	v_rcp_f32_e32 v217, v217
	s_nop 0
	v_pk_mul_f32 v[156:157], v[216:217], v[156:157]
	v_pk_mul_f32 v[2:3], v[2:3], v[156:157]
	s_waitcnt lgkmcnt(0)
	v_lshlrev_b32_e32 v160, 16, v197
	v_and_b32_e32 v161, 0xffff0000, v197
	v_lshlrev_b32_e32 v158, 16, v193
	v_and_b32_e32 v159, 0xffff0000, v193
	v_max_f32_e32 v160, v160, v160
	v_max_f32_e32 v161, v161, v161
	v_max_f32_e32 v160, 0xda24260, v160
	v_max_f32_e32 v161, 0xda24260, v161
	v_rcp_f32_e32 v160, v160
	v_rcp_f32_e32 v161, v161
	s_nop 0
	v_pk_mul_f32 v[158:159], v[160:161], v[158:159]
	v_pk_mul_f32 v[4:5], v[4:5], v[158:159]
	s_branch .Lgate_epi_done
; #define GAS __attribute__((address_space(1)))
; __device__ __forceinline__ float fast_rcp(float x) { return __builtin_amdgcn_rcpf(x); }
; __device__ __forceinline__ v4u tr4(int a, v4u x) { return (v4u){bperm(a, x.x), bperm(a, x.y), bperm(a, x.z), bperm(a, x.w)}; }
; __device__ __forceinline__ v4u pack8(const f32x4& a, const f32x4& b) { return (v4u){pg8::cvt_pk_bf16(a[0], a[1]), pg8::cvt_pk_bf16(a[2], a[3]), pg8::cvt_pk_bf16(b[0], b[1]), pg8::cvt_pk_bf16(b[2], b[3])}; }
;     __device__ __forceinline__ bool operator()(AccT& acc, const Unit& u, int wr, int wc, int fr, int fq) const {
;     ...
;         for (int ai = 0; ai < 2; ++ai)
; #pragma unroll
;             for (int m = 0; m < 4; ++m) { const size_t r = (size_t)(row0 + ai * 128 + m * 16);
; #pragma unroll
;                 for (int bj = 0; bj < 2; ++bj) {
;                     const v4u ga = tr4(t.push, *(const GAS v4u*)(Gt + r * (3 * D) + n * D + col0 + bj * 128));
;                     float f[8] = {bflo(ga.x), bfhi(ga.x), bflo(ga.y), bfhi(ga.y), bflo(ga.z), bfhi(ga.z), bflo(ga.w), bfhi(ga.w)};
;                     if (n < 2) { const v4u gb = tr4(t.push, *(const GAS v4u*)(Gt + r * (3 * D) + (n + 1) * D + col0 + bj * 128));
;                         const float h[8] = {bflo(gb.x), bfhi(gb.x), bflo(gb.y), bfhi(gb.y), bflo(gb.z), bfhi(gb.z), bflo(gb.w), bfhi(gb.w)};
; #pragma unroll
;                         for (int e = 0; e < 8; ++e) f[e] = f[e] * fast_rcp(fmaxf(h[e], 1e-30f)); }
;                     f32x4 v0 = acc[ai][bj][m][0], v1 = acc[ai][bj][m][1];
;                     v0 = v0 * (f32x4){f[0], f[1], f[2], f[3]}; v1 = v1 * (f32x4){f[4], f[5], f[6], f[7]};
;                     acc[ai][bj][m][0] = v0; acc[ai][bj][m][1] = v1;
;                     if (n == 2) *(GAS v4u*)(mix + r * D + col0 + bj * 128) = tr4(t.pull, pack8(v0, v1));
;                 } }
.Lgate_epi_store:
	v_mov_b64_e32 v[146:147], v[152:153]
	global_load_dwordx4 v[166:169], v[146:147], off
	global_load_dwordx4 v[174:177], v[146:147], off offset:256
	s_mov_b64 s[100:101], 0x18000
	v_lshl_add_u64 v[146:147], v[152:153], 0, s[100:101]
	global_load_dwordx4 v[182:185], v[146:147], off
	global_load_dwordx4 v[190:193], v[146:147], off offset:256
	s_mov_b64 s[100:101], 0x30000
	v_lshl_add_u64 v[146:147], v[152:153], 0, s[100:101]
	global_load_dwordx4 v[198:201], v[146:147], off
	global_load_dwordx4 v[206:209], v[146:147], off offset:256
	s_waitcnt vmcnt(5)
	ds_bpermute_b32 v166, v165, v166
	ds_bpermute_b32 v167, v165, v167
	ds_bpermute_b32 v168, v165, v168
	ds_bpermute_b32 v169, v165, v169
	v_mov_b64_e32 v[144:145], v[148:149]
	s_waitcnt lgkmcnt(3)
	v_lshlrev_b32_e32 v150, 16, v166
	v_and_b32_e32 v151, 0xffff0000, v166
	v_pk_mul_f32 v[126:127], v[126:127], v[150:151]
	s_waitcnt lgkmcnt(2)
	v_lshlrev_b32_e32 v154, 16, v167
	v_and_b32_e32 v155, 0xffff0000, v167
	v_pk_mul_f32 v[128:129], v[128:129], v[154:155]
	s_waitcnt lgkmcnt(1)
	v_lshlrev_b32_e32 v156, 16, v168
	v_and_b32_e32 v157, 0xffff0000, v168
	v_pk_mul_f32 v[122:123], v[122:123], v[156:157]
	s_waitcnt lgkmcnt(0)
	v_lshlrev_b32_e32 v158, 16, v169
	v_and_b32_e32 v159, 0xffff0000, v169
	v_pk_mul_f32 v[124:125], v[124:125], v[158:159]
	v_cvt_pk_bf16_f32 v126, v126, v127
	v_cvt_pk_bf16_f32 v127, v128, v129
	v_cvt_pk_bf16_f32 v128, v122, v123
	v_cvt_pk_bf16_f32 v125, v124, v125
	s_nop 1
	ds_bpermute_b32 v122, v143, v126
	ds_bpermute_b32 v123, v143, v127
	ds_bpermute_b32 v124, v143, v128
	ds_bpermute_b32 v125, v143, v125
	s_waitcnt lgkmcnt(0)
	global_store_dwordx4 v[144:145], v[122:125], off
	s_mov_b64 s[100:101], 0x48000
	v_lshl_add_u64 v[146:147], v[152:153], 0, s[100:101]
	global_load_dwordx4 v[166:169], v[146:147], off
	s_waitcnt vmcnt(6)
	ds_bpermute_b32 v174, v165, v174
	ds_bpermute_b32 v175, v165, v175
	ds_bpermute_b32 v176, v165, v176
	ds_bpermute_b32 v177, v165, v177
	s_waitcnt lgkmcnt(3)
	v_lshlrev_b32_e32 v150, 16, v174
	v_and_b32_e32 v151, 0xffff0000, v174
	v_pk_mul_f32 v[94:95], v[94:95], v[150:151]
	s_waitcnt lgkmcnt(2)
	v_lshlrev_b32_e32 v154, 16, v175
	v_and_b32_e32 v155, 0xffff0000, v175
	v_pk_mul_f32 v[96:97], v[96:97], v[154:155]
	s_waitcnt lgkmcnt(1)
	v_lshlrev_b32_e32 v156, 16, v176
	v_and_b32_e32 v157, 0xffff0000, v176
	v_pk_mul_f32 v[90:91], v[90:91], v[156:157]
	s_waitcnt lgkmcnt(0)
	v_lshlrev_b32_e32 v158, 16, v177
	v_and_b32_e32 v159, 0xffff0000, v177
	v_pk_mul_f32 v[92:93], v[92:93], v[158:159]
	v_cvt_pk_bf16_f32 v94, v94, v95
	v_cvt_pk_bf16_f32 v95, v96, v97
	v_cvt_pk_bf16_f32 v96, v90, v91
	v_cvt_pk_bf16_f32 v93, v92, v93
	s_nop 1
	ds_bpermute_b32 v90, v143, v94
	ds_bpermute_b32 v91, v143, v95
	ds_bpermute_b32 v92, v143, v96
	ds_bpermute_b32 v93, v143, v93
	s_waitcnt lgkmcnt(0)
	global_store_dwordx4 v[144:145], v[90:93], off offset:256
	global_load_dwordx4 v[174:177], v[146:147], off offset:256
	s_waitcnt vmcnt(7)
	ds_bpermute_b32 v182, v165, v182
	ds_bpermute_b32 v183, v165, v183
	ds_bpermute_b32 v184, v165, v184
	ds_bpermute_b32 v185, v165, v185
	s_mov_b64 s[100:101], 0x8000
	v_lshl_add_u64 v[144:145], v[148:149], 0, s[100:101]
	s_waitcnt lgkmcnt(3)
	v_lshlrev_b32_e32 v150, 16, v182
	v_and_b32_e32 v151, 0xffff0000, v182
	v_pk_mul_f32 v[118:119], v[118:119], v[150:151]
	s_waitcnt lgkmcnt(2)
	v_lshlrev_b32_e32 v154, 16, v183
	v_and_b32_e32 v155, 0xffff0000, v183
	v_pk_mul_f32 v[120:121], v[120:121], v[154:155]
	s_waitcnt lgkmcnt(1)
	v_lshlrev_b32_e32 v156, 16, v184
	v_and_b32_e32 v157, 0xffff0000, v184
	v_pk_mul_f32 v[114:115], v[114:115], v[156:157]
	s_waitcnt lgkmcnt(0)
	v_lshlrev_b32_e32 v158, 16, v185
	v_and_b32_e32 v159, 0xffff0000, v185
	v_pk_mul_f32 v[116:117], v[116:117], v[158:159]
	v_cvt_pk_bf16_f32 v118, v118, v119
	v_cvt_pk_bf16_f32 v119, v120, v121
	v_cvt_pk_bf16_f32 v120, v114, v115
	v_cvt_pk_bf16_f32 v117, v116, v117
	s_nop 1
	ds_bpermute_b32 v114, v143, v118
	ds_bpermute_b32 v115, v143, v119
	ds_bpermute_b32 v116, v143, v120
	ds_bpermute_b32 v117, v143, v117
	s_waitcnt lgkmcnt(0)
	global_store_dwordx4 v[144:145], v[114:117], off
	s_mov_b64 s[100:101], 0xc0000
	v_lshl_add_u64 v[146:147], v[152:153], 0, s[100:101]
	global_load_dwordx4 v[182:185], v[146:147], off
	s_waitcnt vmcnt(8)
	ds_bpermute_b32 v190, v165, v190
	ds_bpermute_b32 v191, v165, v191
	ds_bpermute_b32 v192, v165, v192
	ds_bpermute_b32 v193, v165, v193
	s_waitcnt lgkmcnt(3)
	v_lshlrev_b32_e32 v150, 16, v190
	v_and_b32_e32 v151, 0xffff0000, v190
	v_pk_mul_f32 v[86:87], v[86:87], v[150:151]
	s_waitcnt lgkmcnt(2)
	v_lshlrev_b32_e32 v154, 16, v191
	v_and_b32_e32 v155, 0xffff0000, v191
	v_pk_mul_f32 v[88:89], v[88:89], v[154:155]
	s_waitcnt lgkmcnt(1)
	v_lshlrev_b32_e32 v156, 16, v192
	v_and_b32_e32 v157, 0xffff0000, v192
	v_pk_mul_f32 v[82:83], v[82:83], v[156:157]
	s_waitcnt lgkmcnt(0)
	v_lshlrev_b32_e32 v158, 16, v193
	v_and_b32_e32 v159, 0xffff0000, v193
	v_pk_mul_f32 v[84:85], v[84:85], v[158:159]
	v_cvt_pk_bf16_f32 v86, v86, v87
	v_cvt_pk_bf16_f32 v87, v88, v89
	v_cvt_pk_bf16_f32 v88, v82, v83
	v_cvt_pk_bf16_f32 v85, v84, v85
	s_nop 1
	ds_bpermute_b32 v82, v143, v86
	ds_bpermute_b32 v83, v143, v87
	ds_bpermute_b32 v84, v143, v88
	ds_bpermute_b32 v85, v143, v85
	s_waitcnt lgkmcnt(0)
	global_store_dwordx4 v[144:145], v[82:85], off offset:256
	global_load_dwordx4 v[190:193], v[146:147], off offset:256
	s_waitcnt vmcnt(9)
	ds_bpermute_b32 v198, v165, v198
	ds_bpermute_b32 v199, v165, v199
	ds_bpermute_b32 v200, v165, v200
	ds_bpermute_b32 v201, v165, v201
	s_mov_b64 s[100:101], 0x10000
	v_lshl_add_u64 v[144:145], v[148:149], 0, s[100:101]
	s_waitcnt lgkmcnt(3)
; #define GAS __attribute__((address_space(1)))
; __device__ __forceinline__ float fast_rcp(float x) { return __builtin_amdgcn_rcpf(x); }
; __device__ __forceinline__ v4u tr4(int a, v4u x) { return (v4u){bperm(a, x.x), bperm(a, x.y), bperm(a, x.z), bperm(a, x.w)}; }
; __device__ __forceinline__ v4u pack8(const f32x4& a, const f32x4& b) { return (v4u){pg8::cvt_pk_bf16(a[0], a[1]), pg8::cvt_pk_bf16(a[2], a[3]), pg8::cvt_pk_bf16(b[0], b[1]), pg8::cvt_pk_bf16(b[2], b[3])}; }
;     __device__ __forceinline__ bool operator()(AccT& acc, const Unit& u, int wr, int wc, int fr, int fq) const {
;     ...
;         for (int ai = 0; ai < 2; ++ai)
; #pragma unroll
;             for (int m = 0; m < 4; ++m) { const size_t r = (size_t)(row0 + ai * 128 + m * 16);
; #pragma unroll
;                 for (int bj = 0; bj < 2; ++bj) {
;                     const v4u ga = tr4(t.push, *(const GAS v4u*)(Gt + r * (3 * D) + n * D + col0 + bj * 128));
;                     float f[8] = {bflo(ga.x), bfhi(ga.x), bflo(ga.y), bfhi(ga.y), bflo(ga.z), bfhi(ga.z), bflo(ga.w), bfhi(ga.w)};
;                     if (n < 2) { const v4u gb = tr4(t.push, *(const GAS v4u*)(Gt + r * (3 * D) + (n + 1) * D + col0 + bj * 128));
;                         const float h[8] = {bflo(gb.x), bfhi(gb.x), bflo(gb.y), bfhi(gb.y), bflo(gb.z), bfhi(gb.z), bflo(gb.w), bfhi(gb.w)};
; #pragma unroll
;                         for (int e = 0; e < 8; ++e) f[e] = f[e] * fast_rcp(fmaxf(h[e], 1e-30f)); }
;                     f32x4 v0 = acc[ai][bj][m][0], v1 = acc[ai][bj][m][1];
;                     v0 = v0 * (f32x4){f[0], f[1], f[2], f[3]}; v1 = v1 * (f32x4){f[4], f[5], f[6], f[7]};
;                     acc[ai][bj][m][0] = v0; acc[ai][bj][m][1] = v1;
;                     if (n == 2) *(GAS v4u*)(mix + r * D + col0 + bj * 128) = tr4(t.pull, pack8(v0, v1));
;                 } }
	v_lshlrev_b32_e32 v150, 16, v198
	v_and_b32_e32 v151, 0xffff0000, v198
	v_pk_mul_f32 v[110:111], v[110:111], v[150:151]
	s_waitcnt lgkmcnt(2)
	v_lshlrev_b32_e32 v154, 16, v199
	v_and_b32_e32 v155, 0xffff0000, v199
	v_pk_mul_f32 v[112:113], v[112:113], v[154:155]
	s_waitcnt lgkmcnt(1)
	v_lshlrev_b32_e32 v156, 16, v200
	v_and_b32_e32 v157, 0xffff0000, v200
	v_pk_mul_f32 v[106:107], v[106:107], v[156:157]
	s_waitcnt lgkmcnt(0)
	v_lshlrev_b32_e32 v158, 16, v201
	v_and_b32_e32 v159, 0xffff0000, v201
	v_pk_mul_f32 v[108:109], v[108:109], v[158:159]
	v_cvt_pk_bf16_f32 v110, v110, v111
	v_cvt_pk_bf16_f32 v111, v112, v113
	v_cvt_pk_bf16_f32 v112, v106, v107
	v_cvt_pk_bf16_f32 v109, v108, v109
	s_nop 1
	ds_bpermute_b32 v106, v143, v110
	ds_bpermute_b32 v107, v143, v111
	ds_bpermute_b32 v108, v143, v112
	ds_bpermute_b32 v109, v143, v109
	s_waitcnt lgkmcnt(0)
	global_store_dwordx4 v[144:145], v[106:109], off
	s_mov_b64 s[100:101], 0xd8000
	v_lshl_add_u64 v[146:147], v[152:153], 0, s[100:101]
	global_load_dwordx4 v[198:201], v[146:147], off
	s_waitcnt vmcnt(10)
	ds_bpermute_b32 v206, v165, v206
	ds_bpermute_b32 v207, v165, v207
	ds_bpermute_b32 v208, v165, v208
	ds_bpermute_b32 v209, v165, v209
	s_waitcnt lgkmcnt(3)
	v_lshlrev_b32_e32 v150, 16, v206
	v_and_b32_e32 v151, 0xffff0000, v206
	v_pk_mul_f32 v[78:79], v[78:79], v[150:151]
	s_waitcnt lgkmcnt(2)
	v_lshlrev_b32_e32 v154, 16, v207
	v_and_b32_e32 v155, 0xffff0000, v207
	v_pk_mul_f32 v[80:81], v[80:81], v[154:155]
	s_waitcnt lgkmcnt(1)
	v_lshlrev_b32_e32 v156, 16, v208
	v_and_b32_e32 v157, 0xffff0000, v208
	v_pk_mul_f32 v[74:75], v[74:75], v[156:157]
	s_waitcnt lgkmcnt(0)
	v_lshlrev_b32_e32 v158, 16, v209
	v_and_b32_e32 v159, 0xffff0000, v209
	v_pk_mul_f32 v[76:77], v[76:77], v[158:159]
	v_cvt_pk_bf16_f32 v78, v78, v79
	v_cvt_pk_bf16_f32 v79, v80, v81
	v_cvt_pk_bf16_f32 v80, v74, v75
	v_cvt_pk_bf16_f32 v77, v76, v77
	s_nop 1
	ds_bpermute_b32 v74, v143, v78
	ds_bpermute_b32 v75, v143, v79
	ds_bpermute_b32 v76, v143, v80
	ds_bpermute_b32 v77, v143, v77
	s_waitcnt lgkmcnt(0)
	global_store_dwordx4 v[144:145], v[74:77], off offset:256
	global_load_dwordx4 v[206:209], v[146:147], off offset:256
	s_waitcnt vmcnt(10)
	ds_bpermute_b32 v166, v165, v166
	ds_bpermute_b32 v167, v165, v167
	ds_bpermute_b32 v168, v165, v168
	ds_bpermute_b32 v169, v165, v169
	s_mov_b64 s[100:101], 0x18000
	v_lshl_add_u64 v[144:145], v[148:149], 0, s[100:101]
	s_waitcnt lgkmcnt(3)
	v_lshlrev_b32_e32 v150, 16, v166
	v_and_b32_e32 v151, 0xffff0000, v166
	v_pk_mul_f32 v[102:103], v[102:103], v[150:151]
	s_waitcnt lgkmcnt(2)
	v_lshlrev_b32_e32 v154, 16, v167
	v_and_b32_e32 v155, 0xffff0000, v167
	v_pk_mul_f32 v[104:105], v[104:105], v[154:155]
	s_waitcnt lgkmcnt(1)
	v_lshlrev_b32_e32 v156, 16, v168
	v_and_b32_e32 v157, 0xffff0000, v168
	v_pk_mul_f32 v[98:99], v[98:99], v[156:157]
	s_waitcnt lgkmcnt(0)
	v_lshlrev_b32_e32 v158, 16, v169
	v_and_b32_e32 v159, 0xffff0000, v169
	v_pk_mul_f32 v[100:101], v[100:101], v[158:159]
	v_cvt_pk_bf16_f32 v102, v102, v103
	v_cvt_pk_bf16_f32 v103, v104, v105
	v_cvt_pk_bf16_f32 v104, v98, v99
	v_cvt_pk_bf16_f32 v101, v100, v101
	s_nop 1
	ds_bpermute_b32 v98, v143, v102
	ds_bpermute_b32 v99, v143, v103
	ds_bpermute_b32 v100, v143, v104
	ds_bpermute_b32 v101, v143, v101
	s_waitcnt lgkmcnt(0)
	global_store_dwordx4 v[144:145], v[98:101], off
	s_mov_b64 s[100:101], 0xf0000
	v_lshl_add_u64 v[146:147], v[152:153], 0, s[100:101]
	global_load_dwordx4 v[166:169], v[146:147], off
	s_waitcnt vmcnt(10)
	ds_bpermute_b32 v174, v165, v174
	ds_bpermute_b32 v175, v165, v175
	ds_bpermute_b32 v176, v165, v176
	ds_bpermute_b32 v177, v165, v177
	s_waitcnt lgkmcnt(3)
	v_lshlrev_b32_e32 v150, 16, v174
	v_and_b32_e32 v151, 0xffff0000, v174
	v_pk_mul_f32 v[70:71], v[70:71], v[150:151]
	s_waitcnt lgkmcnt(2)
	v_lshlrev_b32_e32 v154, 16, v175
	v_and_b32_e32 v155, 0xffff0000, v175
	v_pk_mul_f32 v[72:73], v[72:73], v[154:155]
	s_waitcnt lgkmcnt(1)
	v_lshlrev_b32_e32 v156, 16, v176
	v_and_b32_e32 v157, 0xffff0000, v176
	v_pk_mul_f32 v[66:67], v[66:67], v[156:157]
	s_waitcnt lgkmcnt(0)
	v_lshlrev_b32_e32 v158, 16, v177
	v_and_b32_e32 v159, 0xffff0000, v177
	v_pk_mul_f32 v[68:69], v[68:69], v[158:159]
	v_cvt_pk_bf16_f32 v70, v70, v71
	v_cvt_pk_bf16_f32 v71, v72, v73
	v_cvt_pk_bf16_f32 v72, v66, v67
	v_cvt_pk_bf16_f32 v69, v68, v69
	s_nop 1
	ds_bpermute_b32 v66, v143, v70
	ds_bpermute_b32 v67, v143, v71
	ds_bpermute_b32 v68, v143, v72
	ds_bpermute_b32 v69, v143, v69
	s_waitcnt lgkmcnt(0)
	global_store_dwordx4 v[144:145], v[66:69], off offset:256
	global_load_dwordx4 v[174:177], v[146:147], off offset:256
	s_waitcnt vmcnt(10)
	ds_bpermute_b32 v182, v165, v182
	ds_bpermute_b32 v183, v165, v183
	ds_bpermute_b32 v184, v165, v184
	ds_bpermute_b32 v185, v165, v185
	s_mov_b64 s[100:101], 0x40000
	v_lshl_add_u64 v[144:145], v[148:149], 0, s[100:101]
	s_waitcnt lgkmcnt(3)
	v_lshlrev_b32_e32 v150, 16, v182
	v_and_b32_e32 v151, 0xffff0000, v182
	v_pk_mul_f32 v[62:63], v[62:63], v[150:151]
	s_waitcnt lgkmcnt(2)
	v_lshlrev_b32_e32 v154, 16, v183
	v_and_b32_e32 v155, 0xffff0000, v183
	v_pk_mul_f32 v[64:65], v[64:65], v[154:155]
	s_waitcnt lgkmcnt(1)
	v_lshlrev_b32_e32 v156, 16, v184
	v_and_b32_e32 v157, 0xffff0000, v184
	v_pk_mul_f32 v[58:59], v[58:59], v[156:157]
	s_waitcnt lgkmcnt(0)
	v_lshlrev_b32_e32 v158, 16, v185
	v_and_b32_e32 v159, 0xffff0000, v185
	v_pk_mul_f32 v[60:61], v[60:61], v[158:159]
	v_cvt_pk_bf16_f32 v62, v62, v63
	v_cvt_pk_bf16_f32 v63, v64, v65
	v_cvt_pk_bf16_f32 v64, v58, v59
	v_cvt_pk_bf16_f32 v61, v60, v61
	s_nop 1
	ds_bpermute_b32 v58, v143, v62
	ds_bpermute_b32 v59, v143, v63
	ds_bpermute_b32 v60, v143, v64
	ds_bpermute_b32 v61, v143, v61
	s_waitcnt lgkmcnt(0)
; #define GAS __attribute__((address_space(1)))
; __device__ __forceinline__ float fast_rcp(float x) { return __builtin_amdgcn_rcpf(x); }
; __device__ __forceinline__ v4u tr4(int a, v4u x) { return (v4u){bperm(a, x.x), bperm(a, x.y), bperm(a, x.z), bperm(a, x.w)}; }
; __device__ __forceinline__ v4u pack8(const f32x4& a, const f32x4& b) { return (v4u){pg8::cvt_pk_bf16(a[0], a[1]), pg8::cvt_pk_bf16(a[2], a[3]), pg8::cvt_pk_bf16(b[0], b[1]), pg8::cvt_pk_bf16(b[2], b[3])}; }
;     __device__ __forceinline__ bool operator()(AccT& acc, const Unit& u, int wr, int wc, int fr, int fq) const {
;     ...
;         for (int ai = 0; ai < 2; ++ai)
; #pragma unroll
;             for (int m = 0; m < 4; ++m) { const size_t r = (size_t)(row0 + ai * 128 + m * 16);
; #pragma unroll
;                 for (int bj = 0; bj < 2; ++bj) {
;                     const v4u ga = tr4(t.push, *(const GAS v4u*)(Gt + r * (3 * D) + n * D + col0 + bj * 128));
;                     float f[8] = {bflo(ga.x), bfhi(ga.x), bflo(ga.y), bfhi(ga.y), bflo(ga.z), bfhi(ga.z), bflo(ga.w), bfhi(ga.w)};
;                     if (n < 2) { const v4u gb = tr4(t.push, *(const GAS v4u*)(Gt + r * (3 * D) + (n + 1) * D + col0 + bj * 128));
;                         const float h[8] = {bflo(gb.x), bfhi(gb.x), bflo(gb.y), bfhi(gb.y), bflo(gb.z), bfhi(gb.z), bflo(gb.w), bfhi(gb.w)};
; #pragma unroll
;                         for (int e = 0; e < 8; ++e) f[e] = f[e] * fast_rcp(fmaxf(h[e], 1e-30f)); }
;                     f32x4 v0 = acc[ai][bj][m][0], v1 = acc[ai][bj][m][1];
;                     v0 = v0 * (f32x4){f[0], f[1], f[2], f[3]}; v1 = v1 * (f32x4){f[4], f[5], f[6], f[7]};
;                     acc[ai][bj][m][0] = v0; acc[ai][bj][m][1] = v1;
;                     if (n == 2) *(GAS v4u*)(mix + r * D + col0 + bj * 128) = tr4(t.pull, pack8(v0, v1));
;                 } }
	global_store_dwordx4 v[144:145], v[58:61], off
	s_mov_b64 s[100:101], 0x108000
	v_lshl_add_u64 v[146:147], v[152:153], 0, s[100:101]
	global_load_dwordx4 v[182:185], v[146:147], off
	s_waitcnt vmcnt(10)
	ds_bpermute_b32 v190, v165, v190
	ds_bpermute_b32 v191, v165, v191
	ds_bpermute_b32 v192, v165, v192
	ds_bpermute_b32 v193, v165, v193
	s_waitcnt lgkmcnt(3)
	v_lshlrev_b32_e32 v150, 16, v190
	v_and_b32_e32 v151, 0xffff0000, v190
	v_pk_mul_f32 v[30:31], v[30:31], v[150:151]
	s_waitcnt lgkmcnt(2)
	v_lshlrev_b32_e32 v154, 16, v191
	v_and_b32_e32 v155, 0xffff0000, v191
	v_pk_mul_f32 v[32:33], v[32:33], v[154:155]
	s_waitcnt lgkmcnt(1)
	v_lshlrev_b32_e32 v156, 16, v192
	v_and_b32_e32 v157, 0xffff0000, v192
	v_pk_mul_f32 v[26:27], v[26:27], v[156:157]
	s_waitcnt lgkmcnt(0)
	v_lshlrev_b32_e32 v158, 16, v193
	v_and_b32_e32 v159, 0xffff0000, v193
	v_pk_mul_f32 v[28:29], v[28:29], v[158:159]
	v_cvt_pk_bf16_f32 v30, v30, v31
	v_cvt_pk_bf16_f32 v31, v32, v33
	v_cvt_pk_bf16_f32 v32, v26, v27
	v_cvt_pk_bf16_f32 v29, v28, v29
	s_nop 1
	ds_bpermute_b32 v26, v143, v30
	ds_bpermute_b32 v27, v143, v31
	ds_bpermute_b32 v28, v143, v32
	ds_bpermute_b32 v29, v143, v29
	s_waitcnt lgkmcnt(0)
	global_store_dwordx4 v[144:145], v[26:29], off offset:256
	global_load_dwordx4 v[190:193], v[146:147], off offset:256
	s_waitcnt vmcnt(10)
	ds_bpermute_b32 v198, v165, v198
	ds_bpermute_b32 v199, v165, v199
	ds_bpermute_b32 v200, v165, v200
	ds_bpermute_b32 v201, v165, v201
	s_mov_b64 s[100:101], 0x48000
	v_lshl_add_u64 v[144:145], v[148:149], 0, s[100:101]
	s_waitcnt lgkmcnt(3)
	v_lshlrev_b32_e32 v150, 16, v198
	v_and_b32_e32 v151, 0xffff0000, v198
	v_pk_mul_f32 v[54:55], v[54:55], v[150:151]
	s_waitcnt lgkmcnt(2)
	v_lshlrev_b32_e32 v154, 16, v199
	v_and_b32_e32 v155, 0xffff0000, v199
	v_pk_mul_f32 v[56:57], v[56:57], v[154:155]
	s_waitcnt lgkmcnt(1)
	v_lshlrev_b32_e32 v156, 16, v200
	v_and_b32_e32 v157, 0xffff0000, v200
	v_pk_mul_f32 v[50:51], v[50:51], v[156:157]
	s_waitcnt lgkmcnt(0)
	v_lshlrev_b32_e32 v158, 16, v201
	v_and_b32_e32 v159, 0xffff0000, v201
	v_pk_mul_f32 v[52:53], v[52:53], v[158:159]
	v_cvt_pk_bf16_f32 v54, v54, v55
	v_cvt_pk_bf16_f32 v55, v56, v57
	v_cvt_pk_bf16_f32 v56, v50, v51
	v_cvt_pk_bf16_f32 v53, v52, v53
	s_nop 1
	ds_bpermute_b32 v50, v143, v54
	ds_bpermute_b32 v51, v143, v55
	ds_bpermute_b32 v52, v143, v56
	ds_bpermute_b32 v53, v143, v53
	s_waitcnt lgkmcnt(0)
	global_store_dwordx4 v[144:145], v[50:53], off
	s_waitcnt vmcnt(9)
	ds_bpermute_b32 v206, v165, v206
	ds_bpermute_b32 v207, v165, v207
	ds_bpermute_b32 v208, v165, v208
	ds_bpermute_b32 v209, v165, v209
	s_waitcnt lgkmcnt(3)
	v_lshlrev_b32_e32 v150, 16, v206
	v_and_b32_e32 v151, 0xffff0000, v206
	v_pk_mul_f32 v[22:23], v[22:23], v[150:151]
	s_waitcnt lgkmcnt(2)
	v_lshlrev_b32_e32 v154, 16, v207
	v_and_b32_e32 v155, 0xffff0000, v207
	v_pk_mul_f32 v[24:25], v[24:25], v[154:155]
	s_waitcnt lgkmcnt(1)
	v_lshlrev_b32_e32 v156, 16, v208
	v_and_b32_e32 v157, 0xffff0000, v208
	v_pk_mul_f32 v[18:19], v[18:19], v[156:157]
	s_waitcnt lgkmcnt(0)
	v_lshlrev_b32_e32 v158, 16, v209
	v_and_b32_e32 v159, 0xffff0000, v209
	v_pk_mul_f32 v[20:21], v[20:21], v[158:159]
	v_cvt_pk_bf16_f32 v22, v22, v23
	v_cvt_pk_bf16_f32 v23, v24, v25
	v_cvt_pk_bf16_f32 v24, v18, v19
	v_cvt_pk_bf16_f32 v21, v20, v21
	s_nop 1
	ds_bpermute_b32 v18, v143, v22
	ds_bpermute_b32 v19, v143, v23
	ds_bpermute_b32 v20, v143, v24
	ds_bpermute_b32 v21, v143, v21
	s_waitcnt lgkmcnt(0)
	global_store_dwordx4 v[144:145], v[18:21], off offset:256
	s_waitcnt vmcnt(8)
	ds_bpermute_b32 v166, v165, v166
	ds_bpermute_b32 v167, v165, v167
	ds_bpermute_b32 v168, v165, v168
	ds_bpermute_b32 v169, v165, v169
	s_mov_b64 s[100:101], 0x50000
	v_lshl_add_u64 v[144:145], v[148:149], 0, s[100:101]
	s_waitcnt lgkmcnt(3)
	v_lshlrev_b32_e32 v150, 16, v166
	v_and_b32_e32 v151, 0xffff0000, v166
	v_pk_mul_f32 v[46:47], v[46:47], v[150:151]
	s_waitcnt lgkmcnt(2)
	v_lshlrev_b32_e32 v154, 16, v167
	v_and_b32_e32 v155, 0xffff0000, v167
	v_pk_mul_f32 v[48:49], v[48:49], v[154:155]
	s_waitcnt lgkmcnt(1)
	v_lshlrev_b32_e32 v156, 16, v168
	v_and_b32_e32 v157, 0xffff0000, v168
	v_pk_mul_f32 v[42:43], v[42:43], v[156:157]
	s_waitcnt lgkmcnt(0)
	v_lshlrev_b32_e32 v158, 16, v169
	v_and_b32_e32 v159, 0xffff0000, v169
	v_pk_mul_f32 v[44:45], v[44:45], v[158:159]
	v_cvt_pk_bf16_f32 v46, v46, v47
	v_cvt_pk_bf16_f32 v47, v48, v49
	v_cvt_pk_bf16_f32 v48, v42, v43
	v_cvt_pk_bf16_f32 v45, v44, v45
	s_nop 1
	ds_bpermute_b32 v42, v143, v46
	ds_bpermute_b32 v43, v143, v47
	ds_bpermute_b32 v44, v143, v48
	ds_bpermute_b32 v45, v143, v45
	s_waitcnt lgkmcnt(0)
	global_store_dwordx4 v[144:145], v[42:45], off
	s_waitcnt vmcnt(7)
	ds_bpermute_b32 v174, v165, v174
	ds_bpermute_b32 v175, v165, v175
	ds_bpermute_b32 v176, v165, v176
	ds_bpermute_b32 v177, v165, v177
	s_waitcnt lgkmcnt(3)
	v_lshlrev_b32_e32 v150, 16, v174
	v_and_b32_e32 v151, 0xffff0000, v174
	v_pk_mul_f32 v[14:15], v[14:15], v[150:151]
	s_waitcnt lgkmcnt(2)
	v_lshlrev_b32_e32 v154, 16, v175
	v_and_b32_e32 v155, 0xffff0000, v175
	v_pk_mul_f32 v[16:17], v[16:17], v[154:155]
	s_waitcnt lgkmcnt(1)
	v_lshlrev_b32_e32 v156, 16, v176
	v_and_b32_e32 v157, 0xffff0000, v176
	v_pk_mul_f32 v[10:11], v[10:11], v[156:157]
	s_waitcnt lgkmcnt(0)
	v_lshlrev_b32_e32 v158, 16, v177
	v_and_b32_e32 v159, 0xffff0000, v177
	v_pk_mul_f32 v[12:13], v[12:13], v[158:159]
	v_cvt_pk_bf16_f32 v14, v14, v15
	v_cvt_pk_bf16_f32 v15, v16, v17
	v_cvt_pk_bf16_f32 v16, v10, v11
	v_cvt_pk_bf16_f32 v13, v12, v13
	s_nop 1
	ds_bpermute_b32 v10, v143, v14
	ds_bpermute_b32 v11, v143, v15
	ds_bpermute_b32 v12, v143, v16
	ds_bpermute_b32 v13, v143, v13
	s_waitcnt lgkmcnt(0)
; #define GAS __attribute__((address_space(1)))
; __device__ __forceinline__ float fast_rcp(float x) { return __builtin_amdgcn_rcpf(x); }
; __device__ __forceinline__ v4u tr4(int a, v4u x) { return (v4u){bperm(a, x.x), bperm(a, x.y), bperm(a, x.z), bperm(a, x.w)}; }
; __device__ __forceinline__ v4u pack8(const f32x4& a, const f32x4& b) { return (v4u){pg8::cvt_pk_bf16(a[0], a[1]), pg8::cvt_pk_bf16(a[2], a[3]), pg8::cvt_pk_bf16(b[0], b[1]), pg8::cvt_pk_bf16(b[2], b[3])}; }
; template <class Epi, class Sched, bool ALIGN_EPI = false, bool SP2 = false>
; __device__ __forceinline__ void gemm_phase(PG8_LAS unsigned char* lds, const Gemm g, const Sched& S, const Epi& E, const int wave_id) {
;     ...
;         if (!keep_acc) {
; #pragma unroll
;         for (int a = 0; a < 2; ++a)
; #pragma unroll
;             for (int b = 0; b < 2; ++b)
; #pragma unroll
;                 for (int m = 0; m < 4; ++m)
; #pragma unroll
;                     for (int n = 0; n < 2; ++n) acc[a][b][m][n] = (f32x4){0.f, 0.f, 0.f, 0.f};
;     __device__ __forceinline__ bool operator()(AccT& acc, const Unit& u, int wr, int wc, int fr, int fq) const {
;     ...
;         for (int ai = 0; ai < 2; ++ai)
; #pragma unroll
;             for (int m = 0; m < 4; ++m) { const size_t r = (size_t)(row0 + ai * 128 + m * 16);
; #pragma unroll
;                 for (int bj = 0; bj < 2; ++bj) {
;                     const v4u ga = tr4(t.push, *(const GAS v4u*)(Gt + r * (3 * D) + n * D + col0 + bj * 128));
;                     float f[8] = {bflo(ga.x), bfhi(ga.x), bflo(ga.y), bfhi(ga.y), bflo(ga.z), bfhi(ga.z), bflo(ga.w), bfhi(ga.w)};
;                     if (n < 2) { const v4u gb = tr4(t.push, *(const GAS v4u*)(Gt + r * (3 * D) + (n + 1) * D + col0 + bj * 128));
;                         const float h[8] = {bflo(gb.x), bfhi(gb.x), bflo(gb.y), bfhi(gb.y), bflo(gb.z), bfhi(gb.z), bflo(gb.w), bfhi(gb.w)};
; #pragma unroll
;                         for (int e = 0; e < 8; ++e) f[e] = f[e] * fast_rcp(fmaxf(h[e], 1e-30f)); }
;                     f32x4 v0 = acc[ai][bj][m][0], v1 = acc[ai][bj][m][1];
;                     v0 = v0 * (f32x4){f[0], f[1], f[2], f[3]}; v1 = v1 * (f32x4){f[4], f[5], f[6], f[7]};
;                     acc[ai][bj][m][0] = v0; acc[ai][bj][m][1] = v1;
;                     if (n == 2) *(GAS v4u*)(mix + r * D + col0 + bj * 128) = tr4(t.pull, pack8(v0, v1));
;                 } }
	global_store_dwordx4 v[144:145], v[10:13], off offset:256
	s_waitcnt vmcnt(6)
	ds_bpermute_b32 v182, v165, v182
	ds_bpermute_b32 v183, v165, v183
	ds_bpermute_b32 v184, v165, v184
	ds_bpermute_b32 v185, v165, v185
	s_mov_b64 s[100:101], 0x58000
	v_lshl_add_u64 v[144:145], v[148:149], 0, s[100:101]
	s_waitcnt lgkmcnt(3)
	v_lshlrev_b32_e32 v150, 16, v182
	v_and_b32_e32 v151, 0xffff0000, v182
	v_pk_mul_f32 v[38:39], v[38:39], v[150:151]
	s_waitcnt lgkmcnt(2)
	v_lshlrev_b32_e32 v154, 16, v183
	v_and_b32_e32 v155, 0xffff0000, v183
	v_pk_mul_f32 v[40:41], v[40:41], v[154:155]
	s_waitcnt lgkmcnt(1)
	v_lshlrev_b32_e32 v156, 16, v184
	v_and_b32_e32 v157, 0xffff0000, v184
	v_pk_mul_f32 v[34:35], v[34:35], v[156:157]
	s_waitcnt lgkmcnt(0)
	v_lshlrev_b32_e32 v158, 16, v185
	v_and_b32_e32 v159, 0xffff0000, v185
	v_pk_mul_f32 v[36:37], v[36:37], v[158:159]
	v_cvt_pk_bf16_f32 v38, v38, v39
	v_cvt_pk_bf16_f32 v39, v40, v41
	v_cvt_pk_bf16_f32 v40, v34, v35
	v_cvt_pk_bf16_f32 v37, v36, v37
	s_nop 1
	ds_bpermute_b32 v34, v143, v38
	ds_bpermute_b32 v35, v143, v39
	ds_bpermute_b32 v36, v143, v40
	ds_bpermute_b32 v37, v143, v37
	s_waitcnt lgkmcnt(0)
	global_store_dwordx4 v[144:145], v[34:37], off
	s_waitcnt vmcnt(5)
	ds_bpermute_b32 v190, v165, v190
	ds_bpermute_b32 v191, v165, v191
	ds_bpermute_b32 v192, v165, v192
	ds_bpermute_b32 v193, v165, v193
	s_waitcnt lgkmcnt(3)
	v_lshlrev_b32_e32 v150, 16, v190
	v_and_b32_e32 v151, 0xffff0000, v190
	v_pk_mul_f32 v[6:7], v[6:7], v[150:151]
	s_waitcnt lgkmcnt(2)
	v_lshlrev_b32_e32 v154, 16, v191
	v_and_b32_e32 v155, 0xffff0000, v191
	v_pk_mul_f32 v[8:9], v[8:9], v[154:155]
	s_waitcnt lgkmcnt(1)
	v_lshlrev_b32_e32 v156, 16, v192
	v_and_b32_e32 v157, 0xffff0000, v192
	v_pk_mul_f32 v[2:3], v[2:3], v[156:157]
	s_waitcnt lgkmcnt(0)
	v_lshlrev_b32_e32 v158, 16, v193
	v_and_b32_e32 v159, 0xffff0000, v193
	v_pk_mul_f32 v[4:5], v[4:5], v[158:159]
	v_cvt_pk_bf16_f32 v6, v6, v7
	v_cvt_pk_bf16_f32 v7, v8, v9
	v_cvt_pk_bf16_f32 v8, v2, v3
	v_cvt_pk_bf16_f32 v5, v4, v5
	s_nop 1
	ds_bpermute_b32 v2, v143, v6
	ds_bpermute_b32 v3, v143, v7
	ds_bpermute_b32 v4, v143, v8
	ds_bpermute_b32 v5, v143, v5
	s_waitcnt lgkmcnt(0)
	global_store_dwordx4 v[144:145], v[2:5], off offset:256
.Lgate_epi_done:
.LBB0_1752:
	s_andn2_b64 vcc, exec, s[6:7]
	s_mov_b64 s[6:7], -1
	s_cbranch_vccnz .LBB0_1677
	s_andn2_b64 vcc, exec, s[20:21]
	s_cbranch_vccnz .LBB0_1755
	v_mov_b32_e32 v2, 0
	v_mov_b32_e32 v3, v2
	v_mov_b32_e32 v4, v2
	v_mov_b32_e32 v5, v2
	v_mov_b32_e32 v6, v2
	v_mov_b32_e32 v7, v2
	v_mov_b32_e32 v8, v2
	v_mov_b32_e32 v9, v2
	v_mov_b32_e32 v10, v2
	v_mov_b32_e32 v11, v2
	v_mov_b32_e32 v12, v2
	v_mov_b32_e32 v13, v2
	v_mov_b32_e32 v14, v2
	v_mov_b32_e32 v15, v2
	v_mov_b32_e32 v16, v2
	v_mov_b32_e32 v17, v2
	v_mov_b32_e32 v18, v2
	v_mov_b32_e32 v19, v2
	v_mov_b32_e32 v20, v2
	v_mov_b32_e32 v21, v2
	v_mov_b32_e32 v22, v2
	v_mov_b32_e32 v23, v2
	v_mov_b32_e32 v24, v2
	v_mov_b32_e32 v25, v2
	v_mov_b32_e32 v26, v2
	v_mov_b32_e32 v27, v2
	v_mov_b32_e32 v28, v2
	v_mov_b32_e32 v29, v2
	v_mov_b32_e32 v30, v2
	v_mov_b32_e32 v31, v2
	v_mov_b32_e32 v32, v2
	v_mov_b32_e32 v33, v2
	v_mov_b32_e32 v34, v2
	v_mov_b32_e32 v35, v2
	v_mov_b32_e32 v36, v2
	v_mov_b32_e32 v37, v2
	v_mov_b32_e32 v38, v2
	v_mov_b32_e32 v39, v2
	v_mov_b32_e32 v40, v2
	v_mov_b32_e32 v41, v2
	v_mov_b32_e32 v42, v2
	v_mov_b32_e32 v43, v2
	v_mov_b32_e32 v44, v2
	v_mov_b32_e32 v45, v2
	v_mov_b32_e32 v46, v2
	v_mov_b32_e32 v47, v2
	v_mov_b32_e32 v48, v2
	v_mov_b32_e32 v49, v2
	v_mov_b32_e32 v50, v2
	v_mov_b32_e32 v51, v2
	v_mov_b32_e32 v52, v2
	v_mov_b32_e32 v53, v2
	v_mov_b32_e32 v54, v2
	v_mov_b32_e32 v55, v2
	v_mov_b32_e32 v56, v2
	v_mov_b32_e32 v57, v2
	v_mov_b32_e32 v58, v2
	v_mov_b32_e32 v59, v2
	v_mov_b32_e32 v60, v2
	v_mov_b32_e32 v61, v2
	v_mov_b32_e32 v62, v2
	v_mov_b32_e32 v63, v2
	v_mov_b32_e32 v64, v2
	v_mov_b32_e32 v65, v2
	v_mov_b32_e32 v66, v2
	v_mov_b32_e32 v67, v2
	v_mov_b32_e32 v68, v2
	v_mov_b32_e32 v69, v2
	v_mov_b32_e32 v70, v2
	v_mov_b32_e32 v71, v2
	v_mov_b32_e32 v72, v2
	v_mov_b32_e32 v73, v2
	v_mov_b32_e32 v74, v2
	v_mov_b32_e32 v75, v2
	v_mov_b32_e32 v76, v2
	v_mov_b32_e32 v77, v2
	v_mov_b32_e32 v78, v2
	v_mov_b32_e32 v79, v2
	v_mov_b32_e32 v80, v2
	v_mov_b32_e32 v81, v2
	v_mov_b32_e32 v82, v2
	v_mov_b32_e32 v83, v2
	v_mov_b32_e32 v84, v2
	v_mov_b32_e32 v85, v2
	v_mov_b32_e32 v86, v2
	v_mov_b32_e32 v87, v2
	v_mov_b32_e32 v88, v2
	v_mov_b32_e32 v89, v2
	v_mov_b32_e32 v90, v2
	v_mov_b32_e32 v91, v2
	v_mov_b32_e32 v92, v2
	v_mov_b32_e32 v93, v2
	v_mov_b32_e32 v94, v2
	v_mov_b32_e32 v95, v2
	v_mov_b32_e32 v96, v2
	v_mov_b32_e32 v97, v2
	v_mov_b32_e32 v98, v2
	v_mov_b32_e32 v99, v2
	v_mov_b32_e32 v100, v2
	v_mov_b32_e32 v101, v2
	v_mov_b32_e32 v102, v2
	v_mov_b32_e32 v103, v2
	v_mov_b32_e32 v104, v2
	v_mov_b32_e32 v105, v2
	v_mov_b32_e32 v106, v2
	v_mov_b32_e32 v107, v2
	v_mov_b32_e32 v108, v2
	v_mov_b32_e32 v109, v2
	v_mov_b32_e32 v110, v2
	v_mov_b32_e32 v111, v2
	v_mov_b32_e32 v112, v2
	v_mov_b32_e32 v113, v2
	v_mov_b32_e32 v114, v2
	v_mov_b32_e32 v115, v2
	v_mov_b32_e32 v116, v2
	v_mov_b32_e32 v117, v2
	v_mov_b32_e32 v118, v2
	v_mov_b32_e32 v119, v2
	v_mov_b32_e32 v120, v2
	v_mov_b32_e32 v121, v2
	v_mov_b32_e32 v122, v2
	v_mov_b32_e32 v123, v2
	v_mov_b32_e32 v124, v2
	v_mov_b32_e32 v125, v2
	v_mov_b32_e32 v126, v2
	v_mov_b32_e32 v127, v2
	v_mov_b32_e32 v128, v2
	v_mov_b32_e32 v129, v2
